# non-temporal hint on single-use streaming loads (gate epilogue U tiles, dft_combine partial slices)
# baseline (speedup 1.0000x reference)
.LBB0_160:
	s_cmp_eq_u32 s34, 0
	s_cbranch_scc1 .Lgate_epi_b0
	v_lshl_add_u32 v120, s10, 8, v212
	s_lshl_b32 s10, s38, 8
	v_or_b32_e32 v121, s10, v213
	v_lshlrev_b32_e32 v124, 2, v121
	global_load_dwordx4 v[142:145], v124, s[66:67]
	global_load_dwordx4 v[146:149], v124, s[66:67] offset:16
	global_load_dwordx4 v[150:153], v124, s[66:67] offset:512
	global_load_dwordx4 v[154:157], v124, s[66:67] offset:528
	v_lshlrev_b32_e32 v122, 13, v120
	v_lshl_add_u32 v122, v121, 1, v122
	v_and_b32_e32 v121, 0x3ff, v121
	v_lshlrev_b32_e32 v123, 11, v120
	v_lshl_add_u32 v123, v121, 1, v123
	v_mov_b32_e32 v138, 0xbfb8aa3b
	v_mov_b32_e32 v140, 1.0
	global_load_dwordx4 v[158:161], v122, s[54:55] nt
	global_load_dwordx4 v[162:165], v123, s[58:59]
	v_add_u32_e32 v125, 0x20000, v122
	global_load_dwordx4 v[172:175], v125, s[54:55] nt
	v_add_u32_e32 v125, 0x8000, v123
	global_load_dwordx4 v[176:179], v125, s[58:59]
	v_add_u32_e32 v125, 0x40000, v122
	global_load_dwordx4 v[180:183], v125, s[54:55] nt
	v_add_u32_e32 v125, 0x10000, v123
	global_load_dwordx4 v[184:187], v125, s[58:59]
	v_add_u32_e32 v125, 0x60000, v122
	global_load_dwordx4 v[188:191], v125, s[54:55] nt
	v_add_u32_e32 v125, 0x18000, v123
	global_load_dwordx4 v[192:195], v125, s[58:59]
	v_add_u32_e32 v125, 0x100000, v122
	global_load_dwordx4 v[216:219], v125, s[54:55] nt
	v_add_u32_e32 v125, 0x40000, v123
	global_load_dwordx4 v[220:223], v125, s[58:59]
	v_add_u32_e32 v125, 0x120000, v122
	global_load_dwordx4 v[224:227], v125, s[54:55] nt
	v_add_u32_e32 v125, 0x48000, v123
	global_load_dwordx4 v[228:231], v125, s[58:59]
	v_add_u32_e32 v125, 0x140000, v122
	global_load_dwordx4 v[236:239], v125, s[54:55] nt
	v_add_u32_e32 v125, 0x50000, v123
	global_load_dwordx4 v[240:243], v125, s[58:59]
	v_add_u32_e32 v125, 0x160000, v122
	global_load_dwordx4 v[244:247], v125, s[54:55] nt
	v_add_u32_e32 v125, 0x58000, v123
	global_load_dwordx4 v[248:251], v125, s[58:59]
	global_load_dwordx4 v[252:255], v122, s[54:55] offset:256 nt
	s_waitcnt vmcnt(15)
	v_add_f32_e32 v132, v132, v142
	v_add_f32_e32 v133, v133, v143
	v_add_f32_e32 v134, v134, v144
	v_add_f32_e32 v135, v135, v145
	v_add_f32_e32 v128, v128, v146
	v_add_f32_e32 v129, v129, v147
	v_add_f32_e32 v130, v130, v148
	v_add_f32_e32 v131, v131, v149
	v_mul_f32_e32 v132, 0xbfb8aa3b, v132
	v_mul_f32_e32 v133, 0xbfb8aa3b, v133
	v_mul_f32_e32 v134, 0xbfb8aa3b, v134
	v_mul_f32_e32 v135, 0xbfb8aa3b, v135
	v_mul_f32_e32 v128, 0xbfb8aa3b, v128
	v_mul_f32_e32 v129, 0xbfb8aa3b, v129
	v_mul_f32_e32 v130, 0xbfb8aa3b, v130
	v_mul_f32_e32 v131, 0xbfb8aa3b, v131
	v_exp_f32_e32 v132, v132
	v_exp_f32_e32 v133, v133
	v_exp_f32_e32 v134, v134
	v_exp_f32_e32 v135, v135
	v_exp_f32_e32 v128, v128
	v_exp_f32_e32 v129, v129
	v_exp_f32_e32 v130, v130
	v_exp_f32_e32 v131, v131
	v_add_f32_e32 v132, 1.0, v132
	v_add_f32_e32 v133, 1.0, v133
	v_add_f32_e32 v134, 1.0, v134
	v_add_f32_e32 v135, 1.0, v135
	v_add_f32_e32 v128, 1.0, v128
	v_add_f32_e32 v129, 1.0, v129
	v_add_f32_e32 v130, 1.0, v130
	v_add_f32_e32 v131, 1.0, v131
	v_rcp_f32_e32 v132, v132
	v_rcp_f32_e32 v133, v133
	v_rcp_f32_e32 v134, v134
	v_rcp_f32_e32 v135, v135
	v_rcp_f32_e32 v128, v128
	v_rcp_f32_e32 v129, v129
	v_rcp_f32_e32 v130, v130
	v_rcp_f32_e32 v131, v131
	v_lshlrev_b32_e32 v127, 16, v158
	v_and_b32_e32 v158, 0xffff0000, v158
	v_lshlrev_b32_e32 v136, 16, v162
	v_and_b32_e32 v162, 0xffff0000, v162
	v_fmac_f32_e32 v136, v132, v127
	v_fmac_f32_e32 v162, v133, v158
	v_cvt_pk_bf16_f32 v162, v136, v162
	v_lshlrev_b32_e32 v127, 16, v159
	v_and_b32_e32 v159, 0xffff0000, v159
	v_lshlrev_b32_e32 v136, 16, v163
	v_and_b32_e32 v163, 0xffff0000, v163
	v_fmac_f32_e32 v136, v134, v127
	v_fmac_f32_e32 v163, v135, v159
	v_cvt_pk_bf16_f32 v163, v136, v163
	v_lshlrev_b32_e32 v127, 16, v160
	v_and_b32_e32 v160, 0xffff0000, v160
	v_lshlrev_b32_e32 v136, 16, v164
	v_and_b32_e32 v164, 0xffff0000, v164
	v_fmac_f32_e32 v136, v128, v127
	v_fmac_f32_e32 v164, v129, v160
	v_cvt_pk_bf16_f32 v164, v136, v164
	v_lshlrev_b32_e32 v127, 16, v161
	v_and_b32_e32 v161, 0xffff0000, v161
	v_lshlrev_b32_e32 v136, 16, v165
	v_and_b32_e32 v165, 0xffff0000, v165
	v_fmac_f32_e32 v136, v130, v127
	v_fmac_f32_e32 v165, v131, v161
	v_cvt_pk_bf16_f32 v165, v136, v165
	global_store_dwordx4 v123, v[162:165], s[58:59]
	global_load_dwordx4 v[132:135], v123, s[58:59] offset:256
	v_add_u32_e32 v125, 0x20000, v122
	global_load_dwordx4 v[128:131], v125, s[54:55] offset:256 nt
	v_add_u32_e32 v125, 0x8000, v123
	global_load_dwordx4 v[158:161], v125, s[58:59] offset:256
	v_add_u32_e32 v125, 0x40000, v122
	global_load_dwordx4 v[162:165], v125, s[54:55] offset:256 nt
	s_waitcnt vmcnt(18)
	v_add_f32_e32 v116, v116, v142
	v_add_f32_e32 v117, v117, v143
	v_add_f32_e32 v118, v118, v144
	v_add_f32_e32 v119, v119, v145
	v_add_f32_e32 v112, v112, v146
	v_add_f32_e32 v113, v113, v147
	v_add_f32_e32 v114, v114, v148
	v_add_f32_e32 v115, v115, v149
	v_mul_f32_e32 v116, 0xbfb8aa3b, v116
	v_mul_f32_e32 v117, 0xbfb8aa3b, v117
	v_mul_f32_e32 v118, 0xbfb8aa3b, v118
	v_mul_f32_e32 v119, 0xbfb8aa3b, v119
	v_mul_f32_e32 v112, 0xbfb8aa3b, v112
	v_mul_f32_e32 v113, 0xbfb8aa3b, v113
	v_mul_f32_e32 v114, 0xbfb8aa3b, v114
	v_mul_f32_e32 v115, 0xbfb8aa3b, v115
	v_exp_f32_e32 v116, v116
	v_exp_f32_e32 v117, v117
	v_exp_f32_e32 v118, v118
	v_exp_f32_e32 v119, v119
	v_exp_f32_e32 v112, v112
	v_exp_f32_e32 v113, v113
	v_exp_f32_e32 v114, v114
	v_exp_f32_e32 v115, v115
	v_add_f32_e32 v116, 1.0, v116
	v_add_f32_e32 v117, 1.0, v117
	v_add_f32_e32 v118, 1.0, v118
	v_add_f32_e32 v119, 1.0, v119
	v_add_f32_e32 v112, 1.0, v112
	v_add_f32_e32 v113, 1.0, v113
	v_add_f32_e32 v114, 1.0, v114
	v_add_f32_e32 v115, 1.0, v115
	v_rcp_f32_e32 v116, v116
	v_rcp_f32_e32 v117, v117
	v_rcp_f32_e32 v118, v118
	v_rcp_f32_e32 v119, v119
	v_rcp_f32_e32 v112, v112
	v_rcp_f32_e32 v113, v113
	v_rcp_f32_e32 v114, v114
	v_rcp_f32_e32 v115, v115
	v_lshlrev_b32_e32 v127, 16, v172
	v_and_b32_e32 v172, 0xffff0000, v172
	v_lshlrev_b32_e32 v136, 16, v176
	v_and_b32_e32 v176, 0xffff0000, v176
	v_fmac_f32_e32 v136, v116, v127
	v_fmac_f32_e32 v176, v117, v172
	v_cvt_pk_bf16_f32 v176, v136, v176
	v_lshlrev_b32_e32 v127, 16, v173
	v_and_b32_e32 v173, 0xffff0000, v173
	v_lshlrev_b32_e32 v136, 16, v177
	v_and_b32_e32 v177, 0xffff0000, v177
	v_fmac_f32_e32 v136, v118, v127
	v_fmac_f32_e32 v177, v119, v173
	v_cvt_pk_bf16_f32 v177, v136, v177
	v_lshlrev_b32_e32 v127, 16, v174
	v_and_b32_e32 v174, 0xffff0000, v174
	v_lshlrev_b32_e32 v136, 16, v178
	v_and_b32_e32 v178, 0xffff0000, v178
	v_fmac_f32_e32 v136, v112, v127
	v_fmac_f32_e32 v178, v113, v174
	v_cvt_pk_bf16_f32 v178, v136, v178
	v_lshlrev_b32_e32 v127, 16, v175
	v_and_b32_e32 v175, 0xffff0000, v175
	v_lshlrev_b32_e32 v136, 16, v179
	v_and_b32_e32 v179, 0xffff0000, v179
	v_fmac_f32_e32 v136, v114, v127
	v_fmac_f32_e32 v179, v115, v175
	v_cvt_pk_bf16_f32 v179, v136, v179
	v_add_u32_e32 v126, 0x8000, v123
	global_store_dwordx4 v126, v[176:179], s[58:59]
	v_add_u32_e32 v125, 0x10000, v123
	global_load_dwordx4 v[116:119], v125, s[58:59] offset:256
	v_add_u32_e32 v125, 0x60000, v122
	global_load_dwordx4 v[112:115], v125, s[54:55] offset:256 nt
	v_add_u32_e32 v125, 0x18000, v123
	global_load_dwordx4 v[172:175], v125, s[58:59] offset:256
	v_add_u32_e32 v125, 0x100000, v122
	global_load_dwordx4 v[176:179], v125, s[54:55] offset:256 nt
	s_waitcnt vmcnt(21)
	v_add_f32_e32 v108, v108, v142
	v_add_f32_e32 v109, v109, v143
	v_add_f32_e32 v110, v110, v144
	v_add_f32_e32 v111, v111, v145
	v_add_f32_e32 v104, v104, v146
	v_add_f32_e32 v105, v105, v147
	v_add_f32_e32 v106, v106, v148
	v_add_f32_e32 v107, v107, v149
	v_mul_f32_e32 v108, 0xbfb8aa3b, v108
	v_mul_f32_e32 v109, 0xbfb8aa3b, v109
	v_mul_f32_e32 v110, 0xbfb8aa3b, v110
	v_mul_f32_e32 v111, 0xbfb8aa3b, v111
	v_mul_f32_e32 v104, 0xbfb8aa3b, v104
	v_mul_f32_e32 v105, 0xbfb8aa3b, v105
	v_mul_f32_e32 v106, 0xbfb8aa3b, v106
	v_mul_f32_e32 v107, 0xbfb8aa3b, v107
	v_exp_f32_e32 v108, v108
	v_exp_f32_e32 v109, v109
	v_exp_f32_e32 v110, v110
	v_exp_f32_e32 v111, v111
	v_exp_f32_e32 v104, v104
	v_exp_f32_e32 v105, v105
	v_exp_f32_e32 v106, v106
	v_exp_f32_e32 v107, v107
	v_add_f32_e32 v108, 1.0, v108
	v_add_f32_e32 v109, 1.0, v109
	v_add_f32_e32 v110, 1.0, v110
	v_add_f32_e32 v111, 1.0, v111
	v_add_f32_e32 v104, 1.0, v104
	v_add_f32_e32 v105, 1.0, v105
	v_add_f32_e32 v106, 1.0, v106
	v_add_f32_e32 v107, 1.0, v107
	v_rcp_f32_e32 v108, v108
	v_rcp_f32_e32 v109, v109
	v_rcp_f32_e32 v110, v110
	v_rcp_f32_e32 v111, v111
	v_rcp_f32_e32 v104, v104
	v_rcp_f32_e32 v105, v105
	v_rcp_f32_e32 v106, v106
	v_rcp_f32_e32 v107, v107
	v_lshlrev_b32_e32 v127, 16, v180
	v_and_b32_e32 v180, 0xffff0000, v180
	v_lshlrev_b32_e32 v136, 16, v184
	v_and_b32_e32 v184, 0xffff0000, v184
	v_fmac_f32_e32 v136, v108, v127
	v_fmac_f32_e32 v184, v109, v180
	v_cvt_pk_bf16_f32 v184, v136, v184
	v_lshlrev_b32_e32 v127, 16, v181
	v_and_b32_e32 v181, 0xffff0000, v181
	v_lshlrev_b32_e32 v136, 16, v185
	v_and_b32_e32 v185, 0xffff0000, v185
	v_fmac_f32_e32 v136, v110, v127
	v_fmac_f32_e32 v185, v111, v181
	v_cvt_pk_bf16_f32 v185, v136, v185
	v_lshlrev_b32_e32 v127, 16, v182
	v_and_b32_e32 v182, 0xffff0000, v182
	v_lshlrev_b32_e32 v136, 16, v186
	v_and_b32_e32 v186, 0xffff0000, v186
	v_fmac_f32_e32 v136, v104, v127
	v_fmac_f32_e32 v186, v105, v182
	v_cvt_pk_bf16_f32 v186, v136, v186
	v_lshlrev_b32_e32 v127, 16, v183
	v_and_b32_e32 v183, 0xffff0000, v183
	v_lshlrev_b32_e32 v136, 16, v187
	v_and_b32_e32 v187, 0xffff0000, v187
	v_fmac_f32_e32 v136, v106, v127
	v_fmac_f32_e32 v187, v107, v183
	v_cvt_pk_bf16_f32 v187, v136, v187
	v_add_u32_e32 v126, 0x10000, v123
	global_store_dwordx4 v126, v[184:187], s[58:59]
	v_add_u32_e32 v125, 0x40000, v123
	global_load_dwordx4 v[108:111], v125, s[58:59] offset:256
	v_add_u32_e32 v125, 0x120000, v122
	global_load_dwordx4 v[104:107], v125, s[54:55] offset:256 nt
	v_add_u32_e32 v125, 0x48000, v123
	global_load_dwordx4 v[180:183], v125, s[58:59] offset:256
	v_add_u32_e32 v125, 0x140000, v122
	global_load_dwordx4 v[184:187], v125, s[54:55] offset:256 nt
	s_waitcnt vmcnt(24)
	v_add_f32_e32 v100, v100, v142
	v_add_f32_e32 v101, v101, v143
	v_add_f32_e32 v102, v102, v144
	v_add_f32_e32 v103, v103, v145
	v_add_f32_e32 v96, v96, v146
	v_add_f32_e32 v97, v97, v147
	v_add_f32_e32 v98, v98, v148
	v_add_f32_e32 v99, v99, v149
	v_mul_f32_e32 v100, 0xbfb8aa3b, v100
	v_mul_f32_e32 v101, 0xbfb8aa3b, v101
	v_mul_f32_e32 v102, 0xbfb8aa3b, v102
	v_mul_f32_e32 v103, 0xbfb8aa3b, v103
	v_mul_f32_e32 v96, 0xbfb8aa3b, v96
	v_mul_f32_e32 v97, 0xbfb8aa3b, v97
	v_mul_f32_e32 v98, 0xbfb8aa3b, v98
	v_mul_f32_e32 v99, 0xbfb8aa3b, v99
	v_exp_f32_e32 v100, v100
	v_exp_f32_e32 v101, v101
	v_exp_f32_e32 v102, v102
	v_exp_f32_e32 v103, v103
	v_exp_f32_e32 v96, v96
	v_exp_f32_e32 v97, v97
	v_exp_f32_e32 v98, v98
	v_exp_f32_e32 v99, v99
	v_add_f32_e32 v100, 1.0, v100
	v_add_f32_e32 v101, 1.0, v101
	v_add_f32_e32 v102, 1.0, v102
	v_add_f32_e32 v103, 1.0, v103
	v_add_f32_e32 v96, 1.0, v96
	v_add_f32_e32 v97, 1.0, v97
	v_add_f32_e32 v98, 1.0, v98
	v_add_f32_e32 v99, 1.0, v99
	v_rcp_f32_e32 v100, v100
	v_rcp_f32_e32 v101, v101
	v_rcp_f32_e32 v102, v102
	v_rcp_f32_e32 v103, v103
	v_rcp_f32_e32 v96, v96
	v_rcp_f32_e32 v97, v97
	v_rcp_f32_e32 v98, v98
	v_rcp_f32_e32 v99, v99
	v_lshlrev_b32_e32 v127, 16, v188
	v_and_b32_e32 v188, 0xffff0000, v188
	v_lshlrev_b32_e32 v136, 16, v192
	v_and_b32_e32 v192, 0xffff0000, v192
	v_fmac_f32_e32 v136, v100, v127
	v_fmac_f32_e32 v192, v101, v188
	v_cvt_pk_bf16_f32 v192, v136, v192
	v_lshlrev_b32_e32 v127, 16, v189
	v_and_b32_e32 v189, 0xffff0000, v189
	v_lshlrev_b32_e32 v136, 16, v193
	v_and_b32_e32 v193, 0xffff0000, v193
	v_fmac_f32_e32 v136, v102, v127
	v_fmac_f32_e32 v193, v103, v189
	v_cvt_pk_bf16_f32 v193, v136, v193
	v_lshlrev_b32_e32 v127, 16, v190
	v_and_b32_e32 v190, 0xffff0000, v190
	v_lshlrev_b32_e32 v136, 16, v194
	v_and_b32_e32 v194, 0xffff0000, v194
	v_fmac_f32_e32 v136, v96, v127
	v_fmac_f32_e32 v194, v97, v190
	v_cvt_pk_bf16_f32 v194, v136, v194
	v_lshlrev_b32_e32 v127, 16, v191
	v_and_b32_e32 v191, 0xffff0000, v191
	v_lshlrev_b32_e32 v136, 16, v195
	v_and_b32_e32 v195, 0xffff0000, v195
	v_fmac_f32_e32 v136, v98, v127
	v_fmac_f32_e32 v195, v99, v191
	v_cvt_pk_bf16_f32 v195, v136, v195
	v_add_u32_e32 v126, 0x18000, v123
	global_store_dwordx4 v126, v[192:195], s[58:59]
	v_add_u32_e32 v125, 0x50000, v123
	global_load_dwordx4 v[100:103], v125, s[58:59] offset:256
	v_add_u32_e32 v125, 0x160000, v122
	global_load_dwordx4 v[96:99], v125, s[54:55] offset:256 nt
	v_add_u32_e32 v125, 0x58000, v123
	global_load_dwordx4 v[188:191], v125, s[58:59] offset:256
	s_waitcnt vmcnt(26)
	v_add_f32_e32 v92, v92, v142
	v_add_f32_e32 v93, v93, v143
	v_add_f32_e32 v94, v94, v144
	v_add_f32_e32 v95, v95, v145
	v_add_f32_e32 v88, v88, v146
	v_add_f32_e32 v89, v89, v147
	v_add_f32_e32 v90, v90, v148
	v_add_f32_e32 v91, v91, v149
	v_mul_f32_e32 v92, 0xbfb8aa3b, v92
	v_mul_f32_e32 v93, 0xbfb8aa3b, v93
	v_mul_f32_e32 v94, 0xbfb8aa3b, v94
	v_mul_f32_e32 v95, 0xbfb8aa3b, v95
	v_mul_f32_e32 v88, 0xbfb8aa3b, v88
	v_mul_f32_e32 v89, 0xbfb8aa3b, v89
	v_mul_f32_e32 v90, 0xbfb8aa3b, v90
	v_mul_f32_e32 v91, 0xbfb8aa3b, v91
	v_exp_f32_e32 v92, v92
	v_exp_f32_e32 v93, v93
	v_exp_f32_e32 v94, v94
	v_exp_f32_e32 v95, v95
	v_exp_f32_e32 v88, v88
	v_exp_f32_e32 v89, v89
	v_exp_f32_e32 v90, v90
	v_exp_f32_e32 v91, v91
	v_add_f32_e32 v92, 1.0, v92
	v_add_f32_e32 v93, 1.0, v93
	v_add_f32_e32 v94, 1.0, v94
	v_add_f32_e32 v95, 1.0, v95
	v_add_f32_e32 v88, 1.0, v88
	v_add_f32_e32 v89, 1.0, v89
	v_add_f32_e32 v90, 1.0, v90
	v_add_f32_e32 v91, 1.0, v91
	v_rcp_f32_e32 v92, v92
	v_rcp_f32_e32 v93, v93
	v_rcp_f32_e32 v94, v94
	v_rcp_f32_e32 v95, v95
	v_rcp_f32_e32 v88, v88
	v_rcp_f32_e32 v89, v89
	v_rcp_f32_e32 v90, v90
	v_rcp_f32_e32 v91, v91
	v_lshlrev_b32_e32 v127, 16, v216
	v_and_b32_e32 v216, 0xffff0000, v216
	v_lshlrev_b32_e32 v136, 16, v220
	v_and_b32_e32 v220, 0xffff0000, v220
	v_fmac_f32_e32 v136, v92, v127
	v_fmac_f32_e32 v220, v93, v216
	v_cvt_pk_bf16_f32 v220, v136, v220
	v_lshlrev_b32_e32 v127, 16, v217
	v_and_b32_e32 v217, 0xffff0000, v217
	v_lshlrev_b32_e32 v136, 16, v221
	v_and_b32_e32 v221, 0xffff0000, v221
	v_fmac_f32_e32 v136, v94, v127
	v_fmac_f32_e32 v221, v95, v217
	v_cvt_pk_bf16_f32 v221, v136, v221
	v_lshlrev_b32_e32 v127, 16, v218
	v_and_b32_e32 v218, 0xffff0000, v218
	v_lshlrev_b32_e32 v136, 16, v222
	v_and_b32_e32 v222, 0xffff0000, v222
	v_fmac_f32_e32 v136, v88, v127
	v_fmac_f32_e32 v222, v89, v218
	v_cvt_pk_bf16_f32 v222, v136, v222
	v_lshlrev_b32_e32 v127, 16, v219
	v_and_b32_e32 v219, 0xffff0000, v219
	v_lshlrev_b32_e32 v136, 16, v223
	v_and_b32_e32 v223, 0xffff0000, v223
	v_fmac_f32_e32 v136, v90, v127
	v_fmac_f32_e32 v223, v91, v219
	v_cvt_pk_bf16_f32 v223, v136, v223
	v_add_u32_e32 v126, 0x40000, v123
	global_store_dwordx4 v126, v[220:223], s[58:59]
	s_waitcnt vmcnt(25)
	v_add_f32_e32 v84, v84, v142
	v_add_f32_e32 v85, v85, v143
	v_add_f32_e32 v86, v86, v144
	v_add_f32_e32 v87, v87, v145
	v_add_f32_e32 v80, v80, v146
	v_add_f32_e32 v81, v81, v147
	v_add_f32_e32 v82, v82, v148
	v_add_f32_e32 v83, v83, v149
	v_mul_f32_e32 v84, 0xbfb8aa3b, v84
	v_mul_f32_e32 v85, 0xbfb8aa3b, v85
	v_mul_f32_e32 v86, 0xbfb8aa3b, v86
	v_mul_f32_e32 v87, 0xbfb8aa3b, v87
	v_mul_f32_e32 v80, 0xbfb8aa3b, v80
	v_mul_f32_e32 v81, 0xbfb8aa3b, v81
	v_mul_f32_e32 v82, 0xbfb8aa3b, v82
	v_mul_f32_e32 v83, 0xbfb8aa3b, v83
	v_exp_f32_e32 v84, v84
	v_exp_f32_e32 v85, v85
	v_exp_f32_e32 v86, v86
	v_exp_f32_e32 v87, v87
	v_exp_f32_e32 v80, v80
	v_exp_f32_e32 v81, v81
	v_exp_f32_e32 v82, v82
	v_exp_f32_e32 v83, v83
	v_add_f32_e32 v84, 1.0, v84
	v_add_f32_e32 v85, 1.0, v85
	v_add_f32_e32 v86, 1.0, v86
	v_add_f32_e32 v87, 1.0, v87
	v_add_f32_e32 v80, 1.0, v80
	v_add_f32_e32 v81, 1.0, v81
	v_add_f32_e32 v82, 1.0, v82
	v_add_f32_e32 v83, 1.0, v83
	v_rcp_f32_e32 v84, v84
	v_rcp_f32_e32 v85, v85
	v_rcp_f32_e32 v86, v86
	v_rcp_f32_e32 v87, v87
	v_rcp_f32_e32 v80, v80
	v_rcp_f32_e32 v81, v81
	v_rcp_f32_e32 v82, v82
	v_rcp_f32_e32 v83, v83
	v_lshlrev_b32_e32 v127, 16, v224
	v_and_b32_e32 v224, 0xffff0000, v224
	v_lshlrev_b32_e32 v136, 16, v228
	v_and_b32_e32 v228, 0xffff0000, v228
	v_fmac_f32_e32 v136, v84, v127
	v_fmac_f32_e32 v228, v85, v224
	v_cvt_pk_bf16_f32 v228, v136, v228
	v_lshlrev_b32_e32 v127, 16, v225
	v_and_b32_e32 v225, 0xffff0000, v225
	v_lshlrev_b32_e32 v136, 16, v229
	v_and_b32_e32 v229, 0xffff0000, v229
	v_fmac_f32_e32 v136, v86, v127
	v_fmac_f32_e32 v229, v87, v225
	v_cvt_pk_bf16_f32 v229, v136, v229
	v_lshlrev_b32_e32 v127, 16, v226
	v_and_b32_e32 v226, 0xffff0000, v226
	v_lshlrev_b32_e32 v136, 16, v230
	v_and_b32_e32 v230, 0xffff0000, v230
	v_fmac_f32_e32 v136, v80, v127
	v_fmac_f32_e32 v230, v81, v226
	v_cvt_pk_bf16_f32 v230, v136, v230
	v_lshlrev_b32_e32 v127, 16, v227
	v_and_b32_e32 v227, 0xffff0000, v227
	v_lshlrev_b32_e32 v136, 16, v231
	v_and_b32_e32 v231, 0xffff0000, v231
	v_fmac_f32_e32 v136, v82, v127
	v_fmac_f32_e32 v231, v83, v227
	v_cvt_pk_bf16_f32 v231, v136, v231
	v_add_u32_e32 v126, 0x48000, v123
	global_store_dwordx4 v126, v[228:231], s[58:59]
	s_waitcnt vmcnt(24)
	v_add_f32_e32 v76, v76, v142
	v_add_f32_e32 v77, v77, v143
	v_add_f32_e32 v78, v78, v144
	v_add_f32_e32 v79, v79, v145
	v_add_f32_e32 v72, v72, v146
	v_add_f32_e32 v73, v73, v147
	v_add_f32_e32 v74, v74, v148
	v_add_f32_e32 v75, v75, v149
	v_mul_f32_e32 v76, 0xbfb8aa3b, v76
	v_mul_f32_e32 v77, 0xbfb8aa3b, v77
	v_mul_f32_e32 v78, 0xbfb8aa3b, v78
	v_mul_f32_e32 v79, 0xbfb8aa3b, v79
	v_mul_f32_e32 v72, 0xbfb8aa3b, v72
	v_mul_f32_e32 v73, 0xbfb8aa3b, v73
	v_mul_f32_e32 v74, 0xbfb8aa3b, v74
	v_mul_f32_e32 v75, 0xbfb8aa3b, v75
	v_exp_f32_e32 v76, v76
	v_exp_f32_e32 v77, v77
	v_exp_f32_e32 v78, v78
	v_exp_f32_e32 v79, v79
	v_exp_f32_e32 v72, v72
	v_exp_f32_e32 v73, v73
	v_exp_f32_e32 v74, v74
	v_exp_f32_e32 v75, v75
	v_add_f32_e32 v76, 1.0, v76
	v_add_f32_e32 v77, 1.0, v77
	v_add_f32_e32 v78, 1.0, v78
	v_add_f32_e32 v79, 1.0, v79
	v_add_f32_e32 v72, 1.0, v72
	v_add_f32_e32 v73, 1.0, v73
	v_add_f32_e32 v74, 1.0, v74
	v_add_f32_e32 v75, 1.0, v75
	v_rcp_f32_e32 v76, v76
	v_rcp_f32_e32 v77, v77
	v_rcp_f32_e32 v78, v78
	v_rcp_f32_e32 v79, v79
	v_rcp_f32_e32 v72, v72
	v_rcp_f32_e32 v73, v73
	v_rcp_f32_e32 v74, v74
	v_rcp_f32_e32 v75, v75
	v_lshlrev_b32_e32 v127, 16, v236
	v_and_b32_e32 v236, 0xffff0000, v236
	v_lshlrev_b32_e32 v136, 16, v240
	v_and_b32_e32 v240, 0xffff0000, v240
	v_fmac_f32_e32 v136, v76, v127
	v_fmac_f32_e32 v240, v77, v236
	v_cvt_pk_bf16_f32 v240, v136, v240
	v_lshlrev_b32_e32 v127, 16, v237
	v_and_b32_e32 v237, 0xffff0000, v237
	v_lshlrev_b32_e32 v136, 16, v241
	v_and_b32_e32 v241, 0xffff0000, v241
	v_fmac_f32_e32 v136, v78, v127
	v_fmac_f32_e32 v241, v79, v237
	v_cvt_pk_bf16_f32 v241, v136, v241
	v_lshlrev_b32_e32 v127, 16, v238
	v_and_b32_e32 v238, 0xffff0000, v238
	v_lshlrev_b32_e32 v136, 16, v242
	v_and_b32_e32 v242, 0xffff0000, v242
	v_fmac_f32_e32 v136, v72, v127
	v_fmac_f32_e32 v242, v73, v238
	v_cvt_pk_bf16_f32 v242, v136, v242
	v_lshlrev_b32_e32 v127, 16, v239
	v_and_b32_e32 v239, 0xffff0000, v239
	v_lshlrev_b32_e32 v136, 16, v243
	v_and_b32_e32 v243, 0xffff0000, v243
	v_fmac_f32_e32 v136, v74, v127
	v_fmac_f32_e32 v243, v75, v239
	v_cvt_pk_bf16_f32 v243, v136, v243
	v_add_u32_e32 v126, 0x50000, v123
	global_store_dwordx4 v126, v[240:243], s[58:59]
	s_waitcnt vmcnt(23)
	v_add_f32_e32 v68, v68, v142
	v_add_f32_e32 v69, v69, v143
	v_add_f32_e32 v70, v70, v144
	v_add_f32_e32 v71, v71, v145
	v_add_f32_e32 v64, v64, v146
	v_add_f32_e32 v65, v65, v147
	v_add_f32_e32 v66, v66, v148
	v_add_f32_e32 v67, v67, v149
	v_mul_f32_e32 v68, 0xbfb8aa3b, v68
	v_mul_f32_e32 v69, 0xbfb8aa3b, v69
	v_mul_f32_e32 v70, 0xbfb8aa3b, v70
	v_mul_f32_e32 v71, 0xbfb8aa3b, v71
	v_mul_f32_e32 v64, 0xbfb8aa3b, v64
	v_mul_f32_e32 v65, 0xbfb8aa3b, v65
	v_mul_f32_e32 v66, 0xbfb8aa3b, v66
	v_mul_f32_e32 v67, 0xbfb8aa3b, v67
	v_exp_f32_e32 v68, v68
	v_exp_f32_e32 v69, v69
	v_exp_f32_e32 v70, v70
	v_exp_f32_e32 v71, v71
	v_exp_f32_e32 v64, v64
	v_exp_f32_e32 v65, v65
	v_exp_f32_e32 v66, v66
	v_exp_f32_e32 v67, v67
	v_add_f32_e32 v68, 1.0, v68
	v_add_f32_e32 v69, 1.0, v69
	v_add_f32_e32 v70, 1.0, v70
	v_add_f32_e32 v71, 1.0, v71
	v_add_f32_e32 v64, 1.0, v64
	v_add_f32_e32 v65, 1.0, v65
	v_add_f32_e32 v66, 1.0, v66
	v_add_f32_e32 v67, 1.0, v67
	v_rcp_f32_e32 v68, v68
	v_rcp_f32_e32 v69, v69
	v_rcp_f32_e32 v70, v70
	v_rcp_f32_e32 v71, v71
	v_rcp_f32_e32 v64, v64
	v_rcp_f32_e32 v65, v65
	v_rcp_f32_e32 v66, v66
	v_rcp_f32_e32 v67, v67
	v_lshlrev_b32_e32 v127, 16, v244
	v_and_b32_e32 v244, 0xffff0000, v244
	v_lshlrev_b32_e32 v136, 16, v248
	v_and_b32_e32 v248, 0xffff0000, v248
	v_fmac_f32_e32 v136, v68, v127
	v_fmac_f32_e32 v248, v69, v244
	v_cvt_pk_bf16_f32 v248, v136, v248
	v_lshlrev_b32_e32 v127, 16, v245
	v_and_b32_e32 v245, 0xffff0000, v245
	v_lshlrev_b32_e32 v136, 16, v249
	v_and_b32_e32 v249, 0xffff0000, v249
	v_fmac_f32_e32 v136, v70, v127
	v_fmac_f32_e32 v249, v71, v245
	v_cvt_pk_bf16_f32 v249, v136, v249
	v_lshlrev_b32_e32 v127, 16, v246
	v_and_b32_e32 v246, 0xffff0000, v246
	v_lshlrev_b32_e32 v136, 16, v250
	v_and_b32_e32 v250, 0xffff0000, v250
	v_fmac_f32_e32 v136, v64, v127
	v_fmac_f32_e32 v250, v65, v246
	v_cvt_pk_bf16_f32 v250, v136, v250
	v_lshlrev_b32_e32 v127, 16, v247
	v_and_b32_e32 v247, 0xffff0000, v247
	v_lshlrev_b32_e32 v136, 16, v251
	v_and_b32_e32 v251, 0xffff0000, v251
	v_fmac_f32_e32 v136, v66, v127
	v_fmac_f32_e32 v251, v67, v247
	v_cvt_pk_bf16_f32 v251, v136, v251
	v_add_u32_e32 v126, 0x58000, v123
	global_store_dwordx4 v126, v[248:251], s[58:59]
	s_waitcnt vmcnt(21)
	v_add_f32_e32 v60, v60, v150
	v_add_f32_e32 v61, v61, v151
	v_add_f32_e32 v62, v62, v152
	v_add_f32_e32 v63, v63, v153
	v_add_f32_e32 v56, v56, v154
	v_add_f32_e32 v57, v57, v155
	v_add_f32_e32 v58, v58, v156
	v_add_f32_e32 v59, v59, v157
	v_mul_f32_e32 v60, 0xbfb8aa3b, v60
	v_mul_f32_e32 v61, 0xbfb8aa3b, v61
	v_mul_f32_e32 v62, 0xbfb8aa3b, v62
	v_mul_f32_e32 v63, 0xbfb8aa3b, v63
	v_mul_f32_e32 v56, 0xbfb8aa3b, v56
	v_mul_f32_e32 v57, 0xbfb8aa3b, v57
	v_mul_f32_e32 v58, 0xbfb8aa3b, v58
	v_mul_f32_e32 v59, 0xbfb8aa3b, v59
	v_exp_f32_e32 v60, v60
	v_exp_f32_e32 v61, v61
	v_exp_f32_e32 v62, v62
	v_exp_f32_e32 v63, v63
	v_exp_f32_e32 v56, v56
	v_exp_f32_e32 v57, v57
	v_exp_f32_e32 v58, v58
	v_exp_f32_e32 v59, v59
	v_add_f32_e32 v60, 1.0, v60
	v_add_f32_e32 v61, 1.0, v61
	v_add_f32_e32 v62, 1.0, v62
	v_add_f32_e32 v63, 1.0, v63
	v_add_f32_e32 v56, 1.0, v56
	v_add_f32_e32 v57, 1.0, v57
	v_add_f32_e32 v58, 1.0, v58
	v_add_f32_e32 v59, 1.0, v59
	v_rcp_f32_e32 v60, v60
	v_rcp_f32_e32 v61, v61
	v_rcp_f32_e32 v62, v62
	v_rcp_f32_e32 v63, v63
	v_rcp_f32_e32 v56, v56
	v_rcp_f32_e32 v57, v57
	v_rcp_f32_e32 v58, v58
	v_rcp_f32_e32 v59, v59
	v_lshlrev_b32_e32 v127, 16, v252
	v_and_b32_e32 v252, 0xffff0000, v252
	v_lshlrev_b32_e32 v136, 16, v132
	v_and_b32_e32 v132, 0xffff0000, v132
	v_fmac_f32_e32 v136, v60, v127
	v_fmac_f32_e32 v132, v61, v252
	v_cvt_pk_bf16_f32 v132, v136, v132
	v_lshlrev_b32_e32 v127, 16, v253
	v_and_b32_e32 v253, 0xffff0000, v253
	v_lshlrev_b32_e32 v136, 16, v133
	v_and_b32_e32 v133, 0xffff0000, v133
	v_fmac_f32_e32 v136, v62, v127
	v_fmac_f32_e32 v133, v63, v253
	v_cvt_pk_bf16_f32 v133, v136, v133
	v_lshlrev_b32_e32 v127, 16, v254
	v_and_b32_e32 v254, 0xffff0000, v254
	v_lshlrev_b32_e32 v136, 16, v134
	v_and_b32_e32 v134, 0xffff0000, v134
	v_fmac_f32_e32 v136, v56, v127
	v_fmac_f32_e32 v134, v57, v254
	v_cvt_pk_bf16_f32 v134, v136, v134
	v_lshlrev_b32_e32 v127, 16, v255
	v_and_b32_e32 v255, 0xffff0000, v255
	v_lshlrev_b32_e32 v136, 16, v135
	v_and_b32_e32 v135, 0xffff0000, v135
	v_fmac_f32_e32 v136, v58, v127
	v_fmac_f32_e32 v135, v59, v255
	v_cvt_pk_bf16_f32 v135, v136, v135
	global_store_dwordx4 v123, v[132:135], s[58:59] offset:256
	s_waitcnt vmcnt(20)
	v_add_f32_e32 v52, v52, v150
	v_add_f32_e32 v53, v53, v151
	v_add_f32_e32 v54, v54, v152
	v_add_f32_e32 v55, v55, v153
	v_add_f32_e32 v48, v48, v154
	v_add_f32_e32 v49, v49, v155
	v_add_f32_e32 v50, v50, v156
	v_add_f32_e32 v51, v51, v157
	v_mul_f32_e32 v52, 0xbfb8aa3b, v52
	v_mul_f32_e32 v53, 0xbfb8aa3b, v53
	v_mul_f32_e32 v54, 0xbfb8aa3b, v54
	v_mul_f32_e32 v55, 0xbfb8aa3b, v55
	v_mul_f32_e32 v48, 0xbfb8aa3b, v48
	v_mul_f32_e32 v49, 0xbfb8aa3b, v49
	v_mul_f32_e32 v50, 0xbfb8aa3b, v50
	v_mul_f32_e32 v51, 0xbfb8aa3b, v51
	v_exp_f32_e32 v52, v52
	v_exp_f32_e32 v53, v53
	v_exp_f32_e32 v54, v54
	v_exp_f32_e32 v55, v55
	v_exp_f32_e32 v48, v48
	v_exp_f32_e32 v49, v49
	v_exp_f32_e32 v50, v50
	v_exp_f32_e32 v51, v51
	v_add_f32_e32 v52, 1.0, v52
	v_add_f32_e32 v53, 1.0, v53
	v_add_f32_e32 v54, 1.0, v54
	v_add_f32_e32 v55, 1.0, v55
	v_add_f32_e32 v48, 1.0, v48
	v_add_f32_e32 v49, 1.0, v49
	v_add_f32_e32 v50, 1.0, v50
	v_add_f32_e32 v51, 1.0, v51
	v_rcp_f32_e32 v52, v52
	v_rcp_f32_e32 v53, v53
	v_rcp_f32_e32 v54, v54
	v_rcp_f32_e32 v55, v55
	v_rcp_f32_e32 v48, v48
	v_rcp_f32_e32 v49, v49
	v_rcp_f32_e32 v50, v50
	v_rcp_f32_e32 v51, v51
	v_lshlrev_b32_e32 v127, 16, v128
	v_and_b32_e32 v128, 0xffff0000, v128
	v_lshlrev_b32_e32 v136, 16, v158
	v_and_b32_e32 v158, 0xffff0000, v158
	v_fmac_f32_e32 v136, v52, v127
	v_fmac_f32_e32 v158, v53, v128
	v_cvt_pk_bf16_f32 v158, v136, v158
	v_lshlrev_b32_e32 v127, 16, v129
	v_and_b32_e32 v129, 0xffff0000, v129
	v_lshlrev_b32_e32 v136, 16, v159
	v_and_b32_e32 v159, 0xffff0000, v159
	v_fmac_f32_e32 v136, v54, v127
	v_fmac_f32_e32 v159, v55, v129
	v_cvt_pk_bf16_f32 v159, v136, v159
	v_lshlrev_b32_e32 v127, 16, v130
	v_and_b32_e32 v130, 0xffff0000, v130
	v_lshlrev_b32_e32 v136, 16, v160
	v_and_b32_e32 v160, 0xffff0000, v160
	v_fmac_f32_e32 v136, v48, v127
	v_fmac_f32_e32 v160, v49, v130
	v_cvt_pk_bf16_f32 v160, v136, v160
	v_lshlrev_b32_e32 v127, 16, v131
	v_and_b32_e32 v131, 0xffff0000, v131
	v_lshlrev_b32_e32 v136, 16, v161
	v_and_b32_e32 v161, 0xffff0000, v161
	v_fmac_f32_e32 v136, v50, v127
	v_fmac_f32_e32 v161, v51, v131
	v_cvt_pk_bf16_f32 v161, v136, v161
	v_add_u32_e32 v126, 0x8000, v123
	global_store_dwordx4 v126, v[158:161], s[58:59] offset:256
	s_waitcnt vmcnt(18)
	v_add_f32_e32 v44, v44, v150
	v_add_f32_e32 v45, v45, v151
	v_add_f32_e32 v46, v46, v152
	v_add_f32_e32 v47, v47, v153
	v_add_f32_e32 v40, v40, v154
	v_add_f32_e32 v41, v41, v155
	v_add_f32_e32 v42, v42, v156
	v_add_f32_e32 v43, v43, v157
	v_mul_f32_e32 v44, 0xbfb8aa3b, v44
	v_mul_f32_e32 v45, 0xbfb8aa3b, v45
	v_mul_f32_e32 v46, 0xbfb8aa3b, v46
	v_mul_f32_e32 v47, 0xbfb8aa3b, v47
	v_mul_f32_e32 v40, 0xbfb8aa3b, v40
	v_mul_f32_e32 v41, 0xbfb8aa3b, v41
	v_mul_f32_e32 v42, 0xbfb8aa3b, v42
	v_mul_f32_e32 v43, 0xbfb8aa3b, v43
	v_exp_f32_e32 v44, v44
	v_exp_f32_e32 v45, v45
	v_exp_f32_e32 v46, v46
	v_exp_f32_e32 v47, v47
	v_exp_f32_e32 v40, v40
	v_exp_f32_e32 v41, v41
	v_exp_f32_e32 v42, v42
	v_exp_f32_e32 v43, v43
	v_add_f32_e32 v44, 1.0, v44
	v_add_f32_e32 v45, 1.0, v45
	v_add_f32_e32 v46, 1.0, v46
	v_add_f32_e32 v47, 1.0, v47
	v_add_f32_e32 v40, 1.0, v40
	v_add_f32_e32 v41, 1.0, v41
	v_add_f32_e32 v42, 1.0, v42
	v_add_f32_e32 v43, 1.0, v43
	v_rcp_f32_e32 v44, v44
	v_rcp_f32_e32 v45, v45
	v_rcp_f32_e32 v46, v46
	v_rcp_f32_e32 v47, v47
	v_rcp_f32_e32 v40, v40
	v_rcp_f32_e32 v41, v41
	v_rcp_f32_e32 v42, v42
	v_rcp_f32_e32 v43, v43
	v_lshlrev_b32_e32 v127, 16, v162
	v_and_b32_e32 v162, 0xffff0000, v162
	v_lshlrev_b32_e32 v136, 16, v116
	v_and_b32_e32 v116, 0xffff0000, v116
	v_fmac_f32_e32 v136, v44, v127
	v_fmac_f32_e32 v116, v45, v162
	v_cvt_pk_bf16_f32 v116, v136, v116
	v_lshlrev_b32_e32 v127, 16, v163
	v_and_b32_e32 v163, 0xffff0000, v163
	v_lshlrev_b32_e32 v136, 16, v117
	v_and_b32_e32 v117, 0xffff0000, v117
	v_fmac_f32_e32 v136, v46, v127
	v_fmac_f32_e32 v117, v47, v163
	v_cvt_pk_bf16_f32 v117, v136, v117
	v_lshlrev_b32_e32 v127, 16, v164
	v_and_b32_e32 v164, 0xffff0000, v164
	v_lshlrev_b32_e32 v136, 16, v118
	v_and_b32_e32 v118, 0xffff0000, v118
	v_fmac_f32_e32 v136, v40, v127
	v_fmac_f32_e32 v118, v41, v164
	v_cvt_pk_bf16_f32 v118, v136, v118
	v_lshlrev_b32_e32 v127, 16, v165
	v_and_b32_e32 v165, 0xffff0000, v165
	v_lshlrev_b32_e32 v136, 16, v119
	v_and_b32_e32 v119, 0xffff0000, v119
	v_fmac_f32_e32 v136, v42, v127
	v_fmac_f32_e32 v119, v43, v165
	v_cvt_pk_bf16_f32 v119, v136, v119
	v_add_u32_e32 v126, 0x10000, v123
	global_store_dwordx4 v126, v[116:119], s[58:59] offset:256
	s_waitcnt vmcnt(17)
	v_add_f32_e32 v36, v36, v150
	v_add_f32_e32 v37, v37, v151
	v_add_f32_e32 v38, v38, v152
	v_add_f32_e32 v39, v39, v153
	v_add_f32_e32 v32, v32, v154
	v_add_f32_e32 v33, v33, v155
	v_add_f32_e32 v34, v34, v156
	v_add_f32_e32 v35, v35, v157
	v_mul_f32_e32 v36, 0xbfb8aa3b, v36
	v_mul_f32_e32 v37, 0xbfb8aa3b, v37
	v_mul_f32_e32 v38, 0xbfb8aa3b, v38
	v_mul_f32_e32 v39, 0xbfb8aa3b, v39
	v_mul_f32_e32 v32, 0xbfb8aa3b, v32
	v_mul_f32_e32 v33, 0xbfb8aa3b, v33
	v_mul_f32_e32 v34, 0xbfb8aa3b, v34
	v_mul_f32_e32 v35, 0xbfb8aa3b, v35
	v_exp_f32_e32 v36, v36
	v_exp_f32_e32 v37, v37
	v_exp_f32_e32 v38, v38
	v_exp_f32_e32 v39, v39
	v_exp_f32_e32 v32, v32
	v_exp_f32_e32 v33, v33
	v_exp_f32_e32 v34, v34
	v_exp_f32_e32 v35, v35
	v_add_f32_e32 v36, 1.0, v36
	v_add_f32_e32 v37, 1.0, v37
	v_add_f32_e32 v38, 1.0, v38
	v_add_f32_e32 v39, 1.0, v39
	v_add_f32_e32 v32, 1.0, v32
	v_add_f32_e32 v33, 1.0, v33
	v_add_f32_e32 v34, 1.0, v34
	v_add_f32_e32 v35, 1.0, v35
	v_rcp_f32_e32 v36, v36
	v_rcp_f32_e32 v37, v37
	v_rcp_f32_e32 v38, v38
	v_rcp_f32_e32 v39, v39
	v_rcp_f32_e32 v32, v32
	v_rcp_f32_e32 v33, v33
	v_rcp_f32_e32 v34, v34
	v_rcp_f32_e32 v35, v35
	v_lshlrev_b32_e32 v127, 16, v112
	v_and_b32_e32 v112, 0xffff0000, v112
	v_lshlrev_b32_e32 v136, 16, v172
	v_and_b32_e32 v172, 0xffff0000, v172
	v_fmac_f32_e32 v136, v36, v127
	v_fmac_f32_e32 v172, v37, v112
	v_cvt_pk_bf16_f32 v172, v136, v172
	v_lshlrev_b32_e32 v127, 16, v113
	v_and_b32_e32 v113, 0xffff0000, v113
	v_lshlrev_b32_e32 v136, 16, v173
	v_and_b32_e32 v173, 0xffff0000, v173
	v_fmac_f32_e32 v136, v38, v127
	v_fmac_f32_e32 v173, v39, v113
	v_cvt_pk_bf16_f32 v173, v136, v173
	v_lshlrev_b32_e32 v127, 16, v114
	v_and_b32_e32 v114, 0xffff0000, v114
	v_lshlrev_b32_e32 v136, 16, v174
	v_and_b32_e32 v174, 0xffff0000, v174
	v_fmac_f32_e32 v136, v32, v127
	v_fmac_f32_e32 v174, v33, v114
	v_cvt_pk_bf16_f32 v174, v136, v174
	v_lshlrev_b32_e32 v127, 16, v115
	v_and_b32_e32 v115, 0xffff0000, v115
	v_lshlrev_b32_e32 v136, 16, v175
	v_and_b32_e32 v175, 0xffff0000, v175
	v_fmac_f32_e32 v136, v34, v127
	v_fmac_f32_e32 v175, v35, v115
	v_cvt_pk_bf16_f32 v175, v136, v175
	v_add_u32_e32 v126, 0x18000, v123
	global_store_dwordx4 v126, v[172:175], s[58:59] offset:256
	s_waitcnt vmcnt(15)
	v_add_f32_e32 v28, v28, v150
	v_add_f32_e32 v29, v29, v151
	v_add_f32_e32 v30, v30, v152
	v_add_f32_e32 v31, v31, v153
	v_add_f32_e32 v24, v24, v154
	v_add_f32_e32 v25, v25, v155
	v_add_f32_e32 v26, v26, v156
	v_add_f32_e32 v27, v27, v157
	v_mul_f32_e32 v28, 0xbfb8aa3b, v28
	v_mul_f32_e32 v29, 0xbfb8aa3b, v29
	v_mul_f32_e32 v30, 0xbfb8aa3b, v30
	v_mul_f32_e32 v31, 0xbfb8aa3b, v31
	v_mul_f32_e32 v24, 0xbfb8aa3b, v24
	v_mul_f32_e32 v25, 0xbfb8aa3b, v25
	v_mul_f32_e32 v26, 0xbfb8aa3b, v26
	v_mul_f32_e32 v27, 0xbfb8aa3b, v27
	v_exp_f32_e32 v28, v28
	v_exp_f32_e32 v29, v29
	v_exp_f32_e32 v30, v30
	v_exp_f32_e32 v31, v31
	v_exp_f32_e32 v24, v24
	v_exp_f32_e32 v25, v25
	v_exp_f32_e32 v26, v26
	v_exp_f32_e32 v27, v27
	v_add_f32_e32 v28, 1.0, v28
	v_add_f32_e32 v29, 1.0, v29
	v_add_f32_e32 v30, 1.0, v30
	v_add_f32_e32 v31, 1.0, v31
	v_add_f32_e32 v24, 1.0, v24
	v_add_f32_e32 v25, 1.0, v25
	v_add_f32_e32 v26, 1.0, v26
	v_add_f32_e32 v27, 1.0, v27
	v_rcp_f32_e32 v28, v28
	v_rcp_f32_e32 v29, v29
	v_rcp_f32_e32 v30, v30
	v_rcp_f32_e32 v31, v31
	v_rcp_f32_e32 v24, v24
	v_rcp_f32_e32 v25, v25
	v_rcp_f32_e32 v26, v26
	v_rcp_f32_e32 v27, v27
	v_lshlrev_b32_e32 v127, 16, v176
	v_and_b32_e32 v176, 0xffff0000, v176
	v_lshlrev_b32_e32 v136, 16, v108
	v_and_b32_e32 v108, 0xffff0000, v108
	v_fmac_f32_e32 v136, v28, v127
	v_fmac_f32_e32 v108, v29, v176
	v_cvt_pk_bf16_f32 v108, v136, v108
	v_lshlrev_b32_e32 v127, 16, v177
	v_and_b32_e32 v177, 0xffff0000, v177
	v_lshlrev_b32_e32 v136, 16, v109
	v_and_b32_e32 v109, 0xffff0000, v109
	v_fmac_f32_e32 v136, v30, v127
	v_fmac_f32_e32 v109, v31, v177
	v_cvt_pk_bf16_f32 v109, v136, v109
	v_lshlrev_b32_e32 v127, 16, v178
	v_and_b32_e32 v178, 0xffff0000, v178
	v_lshlrev_b32_e32 v136, 16, v110
	v_and_b32_e32 v110, 0xffff0000, v110
	v_fmac_f32_e32 v136, v24, v127
	v_fmac_f32_e32 v110, v25, v178
	v_cvt_pk_bf16_f32 v110, v136, v110
	v_lshlrev_b32_e32 v127, 16, v179
	v_and_b32_e32 v179, 0xffff0000, v179
	v_lshlrev_b32_e32 v136, 16, v111
	v_and_b32_e32 v111, 0xffff0000, v111
	v_fmac_f32_e32 v136, v26, v127
	v_fmac_f32_e32 v111, v27, v179
	v_cvt_pk_bf16_f32 v111, v136, v111
	v_add_u32_e32 v126, 0x40000, v123
	global_store_dwordx4 v126, v[108:111], s[58:59] offset:256
	s_waitcnt vmcnt(14)
	v_add_f32_e32 v20, v20, v150
	v_add_f32_e32 v21, v21, v151
	v_add_f32_e32 v22, v22, v152
	v_add_f32_e32 v23, v23, v153
	v_add_f32_e32 v16, v16, v154
	v_add_f32_e32 v17, v17, v155
	v_add_f32_e32 v18, v18, v156
	v_add_f32_e32 v19, v19, v157
	v_mul_f32_e32 v20, 0xbfb8aa3b, v20
	v_mul_f32_e32 v21, 0xbfb8aa3b, v21
	v_mul_f32_e32 v22, 0xbfb8aa3b, v22
	v_mul_f32_e32 v23, 0xbfb8aa3b, v23
	v_mul_f32_e32 v16, 0xbfb8aa3b, v16
	v_mul_f32_e32 v17, 0xbfb8aa3b, v17
	v_mul_f32_e32 v18, 0xbfb8aa3b, v18
	v_mul_f32_e32 v19, 0xbfb8aa3b, v19
	v_exp_f32_e32 v20, v20
	v_exp_f32_e32 v21, v21
	v_exp_f32_e32 v22, v22
	v_exp_f32_e32 v23, v23
	v_exp_f32_e32 v16, v16
	v_exp_f32_e32 v17, v17
	v_exp_f32_e32 v18, v18
	v_exp_f32_e32 v19, v19
	v_add_f32_e32 v20, 1.0, v20
	v_add_f32_e32 v21, 1.0, v21
	v_add_f32_e32 v22, 1.0, v22
	v_add_f32_e32 v23, 1.0, v23
	v_add_f32_e32 v16, 1.0, v16
	v_add_f32_e32 v17, 1.0, v17
	v_add_f32_e32 v18, 1.0, v18
	v_add_f32_e32 v19, 1.0, v19
	v_rcp_f32_e32 v20, v20
	v_rcp_f32_e32 v21, v21
	v_rcp_f32_e32 v22, v22
	v_rcp_f32_e32 v23, v23
	v_rcp_f32_e32 v16, v16
	v_rcp_f32_e32 v17, v17
	v_rcp_f32_e32 v18, v18
	v_rcp_f32_e32 v19, v19
	v_lshlrev_b32_e32 v127, 16, v104
	v_and_b32_e32 v104, 0xffff0000, v104
	v_lshlrev_b32_e32 v136, 16, v180
	v_and_b32_e32 v180, 0xffff0000, v180
	v_fmac_f32_e32 v136, v20, v127
	v_fmac_f32_e32 v180, v21, v104
	v_cvt_pk_bf16_f32 v180, v136, v180
	v_lshlrev_b32_e32 v127, 16, v105
	v_and_b32_e32 v105, 0xffff0000, v105
	v_lshlrev_b32_e32 v136, 16, v181
	v_and_b32_e32 v181, 0xffff0000, v181
	v_fmac_f32_e32 v136, v22, v127
	v_fmac_f32_e32 v181, v23, v105
	v_cvt_pk_bf16_f32 v181, v136, v181
	v_lshlrev_b32_e32 v127, 16, v106
	v_and_b32_e32 v106, 0xffff0000, v106
	v_lshlrev_b32_e32 v136, 16, v182
	v_and_b32_e32 v182, 0xffff0000, v182
	v_fmac_f32_e32 v136, v16, v127
	v_fmac_f32_e32 v182, v17, v106
	v_cvt_pk_bf16_f32 v182, v136, v182
	v_lshlrev_b32_e32 v127, 16, v107
	v_and_b32_e32 v107, 0xffff0000, v107
	v_lshlrev_b32_e32 v136, 16, v183
	v_and_b32_e32 v183, 0xffff0000, v183
	v_fmac_f32_e32 v136, v18, v127
	v_fmac_f32_e32 v183, v19, v107
	v_cvt_pk_bf16_f32 v183, v136, v183
	v_add_u32_e32 v126, 0x48000, v123
	global_store_dwordx4 v126, v[180:183], s[58:59] offset:256
	s_waitcnt vmcnt(12)
	v_add_f32_e32 v12, v12, v150
	v_add_f32_e32 v13, v13, v151
	v_add_f32_e32 v14, v14, v152
	v_add_f32_e32 v15, v15, v153
	v_add_f32_e32 v8, v8, v154
	v_add_f32_e32 v9, v9, v155
	v_add_f32_e32 v10, v10, v156
	v_add_f32_e32 v11, v11, v157
	v_mul_f32_e32 v12, 0xbfb8aa3b, v12
	v_mul_f32_e32 v13, 0xbfb8aa3b, v13
	v_mul_f32_e32 v14, 0xbfb8aa3b, v14
	v_mul_f32_e32 v15, 0xbfb8aa3b, v15
	v_mul_f32_e32 v8, 0xbfb8aa3b, v8
	v_mul_f32_e32 v9, 0xbfb8aa3b, v9
	v_mul_f32_e32 v10, 0xbfb8aa3b, v10
	v_mul_f32_e32 v11, 0xbfb8aa3b, v11
	v_exp_f32_e32 v12, v12
	v_exp_f32_e32 v13, v13
	v_exp_f32_e32 v14, v14
	v_exp_f32_e32 v15, v15
	v_exp_f32_e32 v8, v8
	v_exp_f32_e32 v9, v9
	v_exp_f32_e32 v10, v10
	v_exp_f32_e32 v11, v11
	v_add_f32_e32 v12, 1.0, v12
	v_add_f32_e32 v13, 1.0, v13
	v_add_f32_e32 v14, 1.0, v14
	v_add_f32_e32 v15, 1.0, v15
	v_add_f32_e32 v8, 1.0, v8
	v_add_f32_e32 v9, 1.0, v9
	v_add_f32_e32 v10, 1.0, v10
	v_add_f32_e32 v11, 1.0, v11
	v_rcp_f32_e32 v12, v12
	v_rcp_f32_e32 v13, v13
	v_rcp_f32_e32 v14, v14
	v_rcp_f32_e32 v15, v15
	v_rcp_f32_e32 v8, v8
	v_rcp_f32_e32 v9, v9
	v_rcp_f32_e32 v10, v10
	v_rcp_f32_e32 v11, v11
	v_lshlrev_b32_e32 v127, 16, v184
	v_and_b32_e32 v184, 0xffff0000, v184
	v_lshlrev_b32_e32 v136, 16, v100
	v_and_b32_e32 v100, 0xffff0000, v100
	v_fmac_f32_e32 v136, v12, v127
	v_fmac_f32_e32 v100, v13, v184
	v_cvt_pk_bf16_f32 v100, v136, v100
	v_lshlrev_b32_e32 v127, 16, v185
	v_and_b32_e32 v185, 0xffff0000, v185
	v_lshlrev_b32_e32 v136, 16, v101
	v_and_b32_e32 v101, 0xffff0000, v101
	v_fmac_f32_e32 v136, v14, v127
	v_fmac_f32_e32 v101, v15, v185
	v_cvt_pk_bf16_f32 v101, v136, v101
	v_lshlrev_b32_e32 v127, 16, v186
	v_and_b32_e32 v186, 0xffff0000, v186
	v_lshlrev_b32_e32 v136, 16, v102
	v_and_b32_e32 v102, 0xffff0000, v102
	v_fmac_f32_e32 v136, v8, v127
	v_fmac_f32_e32 v102, v9, v186
	v_cvt_pk_bf16_f32 v102, v136, v102
	v_lshlrev_b32_e32 v127, 16, v187
	v_and_b32_e32 v187, 0xffff0000, v187
	v_lshlrev_b32_e32 v136, 16, v103
	v_and_b32_e32 v103, 0xffff0000, v103
	v_fmac_f32_e32 v136, v10, v127
	v_fmac_f32_e32 v103, v11, v187
	v_cvt_pk_bf16_f32 v103, v136, v103
	v_add_u32_e32 v126, 0x50000, v123
	global_store_dwordx4 v126, v[100:103], s[58:59] offset:256
	s_waitcnt vmcnt(11)
	v_add_f32_e32 v4, v4, v150
	v_add_f32_e32 v5, v5, v151
	v_add_f32_e32 v6, v6, v152
	v_add_f32_e32 v7, v7, v153
	v_add_f32_e32 v0, v0, v154
	v_add_f32_e32 v1, v1, v155
	v_add_f32_e32 v2, v2, v156
	v_add_f32_e32 v3, v3, v157
	v_mul_f32_e32 v4, 0xbfb8aa3b, v4
	v_mul_f32_e32 v5, 0xbfb8aa3b, v5
	v_mul_f32_e32 v6, 0xbfb8aa3b, v6
	v_mul_f32_e32 v7, 0xbfb8aa3b, v7
	v_mul_f32_e32 v0, 0xbfb8aa3b, v0
	v_mul_f32_e32 v1, 0xbfb8aa3b, v1
	v_mul_f32_e32 v2, 0xbfb8aa3b, v2
	v_mul_f32_e32 v3, 0xbfb8aa3b, v3
	v_exp_f32_e32 v4, v4
	v_exp_f32_e32 v5, v5
	v_exp_f32_e32 v6, v6
	v_exp_f32_e32 v7, v7
	v_exp_f32_e32 v0, v0
	v_exp_f32_e32 v1, v1
	v_exp_f32_e32 v2, v2
	v_exp_f32_e32 v3, v3
	v_add_f32_e32 v4, 1.0, v4
	v_add_f32_e32 v5, 1.0, v5
	v_add_f32_e32 v6, 1.0, v6
	v_add_f32_e32 v7, 1.0, v7
	v_add_f32_e32 v0, 1.0, v0
	v_add_f32_e32 v1, 1.0, v1
	v_add_f32_e32 v2, 1.0, v2
	v_add_f32_e32 v3, 1.0, v3
	v_rcp_f32_e32 v4, v4
	v_rcp_f32_e32 v5, v5
	v_rcp_f32_e32 v6, v6
	v_rcp_f32_e32 v7, v7
	v_rcp_f32_e32 v0, v0
	v_rcp_f32_e32 v1, v1
	v_rcp_f32_e32 v2, v2
	v_rcp_f32_e32 v3, v3
	v_lshlrev_b32_e32 v127, 16, v96
	v_and_b32_e32 v96, 0xffff0000, v96
	v_lshlrev_b32_e32 v136, 16, v188
	v_and_b32_e32 v188, 0xffff0000, v188
	v_fmac_f32_e32 v136, v4, v127
	v_fmac_f32_e32 v188, v5, v96
	v_cvt_pk_bf16_f32 v188, v136, v188
	v_lshlrev_b32_e32 v127, 16, v97
	v_and_b32_e32 v97, 0xffff0000, v97
	v_lshlrev_b32_e32 v136, 16, v189
	v_and_b32_e32 v189, 0xffff0000, v189
	v_fmac_f32_e32 v136, v6, v127
	v_fmac_f32_e32 v189, v7, v97
	v_cvt_pk_bf16_f32 v189, v136, v189
	v_lshlrev_b32_e32 v127, 16, v98
	v_and_b32_e32 v98, 0xffff0000, v98
	v_lshlrev_b32_e32 v136, 16, v190
	v_and_b32_e32 v190, 0xffff0000, v190
	v_fmac_f32_e32 v136, v0, v127
	v_fmac_f32_e32 v190, v1, v98
	v_cvt_pk_bf16_f32 v190, v136, v190
	v_lshlrev_b32_e32 v127, 16, v99
	v_and_b32_e32 v99, 0xffff0000, v99
	v_lshlrev_b32_e32 v136, 16, v191
	v_and_b32_e32 v191, 0xffff0000, v191
	v_fmac_f32_e32 v136, v2, v127
	v_fmac_f32_e32 v191, v3, v99
	v_cvt_pk_bf16_f32 v191, v136, v191
	v_add_u32_e32 v126, 0x58000, v123
	global_store_dwordx4 v126, v[188:191], s[58:59] offset:256
	s_branch .Lgate_epi_done
.Lgate_epi_b0:
	v_lshl_add_u32 v120, s10, 8, v212
	s_lshl_b32 s10, s38, 8
	v_or_b32_e32 v121, s10, v213
	v_lshlrev_b32_e32 v124, 2, v121
	global_load_dwordx4 v[142:145], v124, s[66:67]
	global_load_dwordx4 v[146:149], v124, s[66:67] offset:16
	global_load_dwordx4 v[150:153], v124, s[66:67] offset:512
	global_load_dwordx4 v[154:157], v124, s[66:67] offset:528
	v_lshlrev_b32_e32 v122, 13, v120
	v_lshl_add_u32 v122, v121, 1, v122
	v_and_b32_e32 v121, 0x3ff, v121
	v_lshlrev_b32_e32 v123, 11, v120
	v_lshl_add_u32 v123, v121, 1, v123
	v_mov_b32_e32 v138, 0xbfb8aa3b
	v_mov_b32_e32 v140, 1.0
	global_load_dwordx4 v[158:161], v122, s[54:55] nt
	v_add_u32_e32 v125, 0x20000, v122
	global_load_dwordx4 v[162:165], v125, s[54:55] nt
	v_add_u32_e32 v125, 0x40000, v122
	global_load_dwordx4 v[172:175], v125, s[54:55] nt
	v_add_u32_e32 v125, 0x60000, v122
	global_load_dwordx4 v[176:179], v125, s[54:55] nt
	v_add_u32_e32 v125, 0x100000, v122
	global_load_dwordx4 v[180:183], v125, s[54:55] nt
	v_add_u32_e32 v125, 0x120000, v122
	global_load_dwordx4 v[184:187], v125, s[54:55] nt
	v_add_u32_e32 v125, 0x140000, v122
	global_load_dwordx4 v[188:191], v125, s[54:55] nt
	v_add_u32_e32 v125, 0x160000, v122
	global_load_dwordx4 v[192:195], v125, s[54:55] nt
	global_load_dwordx4 v[216:219], v122, s[54:55] offset:256 nt
	v_add_u32_e32 v125, 0x20000, v122
	global_load_dwordx4 v[220:223], v125, s[54:55] offset:256 nt
	v_add_u32_e32 v125, 0x40000, v122
	global_load_dwordx4 v[224:227], v125, s[54:55] offset:256 nt
	v_add_u32_e32 v125, 0x60000, v122
	global_load_dwordx4 v[228:231], v125, s[54:55] offset:256 nt
	v_add_u32_e32 v125, 0x100000, v122
	global_load_dwordx4 v[236:239], v125, s[54:55] offset:256 nt
	v_add_u32_e32 v125, 0x120000, v122
	global_load_dwordx4 v[240:243], v125, s[54:55] offset:256 nt
	v_add_u32_e32 v125, 0x140000, v122
	global_load_dwordx4 v[244:247], v125, s[54:55] offset:256 nt
	v_add_u32_e32 v125, 0x160000, v122
	global_load_dwordx4 v[248:251], v125, s[54:55] offset:256 nt
	s_waitcnt vmcnt(15)
	v_add_f32_e32 v132, v132, v142
	v_add_f32_e32 v133, v133, v143
	v_add_f32_e32 v134, v134, v144
	v_add_f32_e32 v135, v135, v145
	v_add_f32_e32 v128, v128, v146
	v_add_f32_e32 v129, v129, v147
	v_add_f32_e32 v130, v130, v148
	v_add_f32_e32 v131, v131, v149
	v_mul_f32_e32 v132, 0xbfb8aa3b, v132
	v_mul_f32_e32 v133, 0xbfb8aa3b, v133
	v_mul_f32_e32 v134, 0xbfb8aa3b, v134
	v_mul_f32_e32 v135, 0xbfb8aa3b, v135
	v_mul_f32_e32 v128, 0xbfb8aa3b, v128
	v_mul_f32_e32 v129, 0xbfb8aa3b, v129
	v_mul_f32_e32 v130, 0xbfb8aa3b, v130
	v_mul_f32_e32 v131, 0xbfb8aa3b, v131
	v_exp_f32_e32 v132, v132
	v_exp_f32_e32 v133, v133
	v_exp_f32_e32 v134, v134
	v_exp_f32_e32 v135, v135
	v_exp_f32_e32 v128, v128
	v_exp_f32_e32 v129, v129
	v_exp_f32_e32 v130, v130
	v_exp_f32_e32 v131, v131
	v_add_f32_e32 v132, 1.0, v132
	v_add_f32_e32 v133, 1.0, v133
	v_add_f32_e32 v134, 1.0, v134
	v_add_f32_e32 v135, 1.0, v135
	v_add_f32_e32 v128, 1.0, v128
	v_add_f32_e32 v129, 1.0, v129
	v_add_f32_e32 v130, 1.0, v130
	v_add_f32_e32 v131, 1.0, v131
	v_rcp_f32_e32 v132, v132
	v_rcp_f32_e32 v133, v133
	v_rcp_f32_e32 v134, v134
	v_rcp_f32_e32 v135, v135
	v_rcp_f32_e32 v128, v128
	v_rcp_f32_e32 v129, v129
	v_rcp_f32_e32 v130, v130
	v_rcp_f32_e32 v131, v131
	v_lshlrev_b32_e32 v127, 16, v158
	v_and_b32_e32 v158, 0xffff0000, v158
	v_mul_f32_e32 v127, v132, v127
	v_mul_f32_e32 v158, v133, v158
	v_cvt_pk_bf16_f32 v158, v127, v158
	v_lshlrev_b32_e32 v127, 16, v159
	v_and_b32_e32 v159, 0xffff0000, v159
	v_mul_f32_e32 v127, v134, v127
	v_mul_f32_e32 v159, v135, v159
	v_cvt_pk_bf16_f32 v159, v127, v159
	v_lshlrev_b32_e32 v127, 16, v160
	v_and_b32_e32 v160, 0xffff0000, v160
	v_mul_f32_e32 v127, v128, v127
	v_mul_f32_e32 v160, v129, v160
	v_cvt_pk_bf16_f32 v160, v127, v160
	v_lshlrev_b32_e32 v127, 16, v161
	v_and_b32_e32 v161, 0xffff0000, v161
	v_mul_f32_e32 v127, v130, v127
	v_mul_f32_e32 v161, v131, v161
	v_cvt_pk_bf16_f32 v161, v127, v161
	global_store_dwordx4 v123, v[158:161], s[58:59]
	s_waitcnt vmcnt(15)
	v_add_f32_e32 v116, v116, v142
	v_add_f32_e32 v117, v117, v143
	v_add_f32_e32 v118, v118, v144
	v_add_f32_e32 v119, v119, v145
	v_add_f32_e32 v112, v112, v146
	v_add_f32_e32 v113, v113, v147
	v_add_f32_e32 v114, v114, v148
	v_add_f32_e32 v115, v115, v149
	v_mul_f32_e32 v116, 0xbfb8aa3b, v116
	v_mul_f32_e32 v117, 0xbfb8aa3b, v117
	v_mul_f32_e32 v118, 0xbfb8aa3b, v118
	v_mul_f32_e32 v119, 0xbfb8aa3b, v119
	v_mul_f32_e32 v112, 0xbfb8aa3b, v112
	v_mul_f32_e32 v113, 0xbfb8aa3b, v113
	v_mul_f32_e32 v114, 0xbfb8aa3b, v114
	v_mul_f32_e32 v115, 0xbfb8aa3b, v115
	v_exp_f32_e32 v116, v116
	v_exp_f32_e32 v117, v117
	v_exp_f32_e32 v118, v118
	v_exp_f32_e32 v119, v119
	v_exp_f32_e32 v112, v112
	v_exp_f32_e32 v113, v113
	v_exp_f32_e32 v114, v114
	v_exp_f32_e32 v115, v115
	v_add_f32_e32 v116, 1.0, v116
	v_add_f32_e32 v117, 1.0, v117
	v_add_f32_e32 v118, 1.0, v118
	v_add_f32_e32 v119, 1.0, v119
	v_add_f32_e32 v112, 1.0, v112
	v_add_f32_e32 v113, 1.0, v113
	v_add_f32_e32 v114, 1.0, v114
	v_add_f32_e32 v115, 1.0, v115
	v_rcp_f32_e32 v116, v116
	v_rcp_f32_e32 v117, v117
	v_rcp_f32_e32 v118, v118
	v_rcp_f32_e32 v119, v119
	v_rcp_f32_e32 v112, v112
	v_rcp_f32_e32 v113, v113
	v_rcp_f32_e32 v114, v114
	v_rcp_f32_e32 v115, v115
	v_lshlrev_b32_e32 v127, 16, v162
	v_and_b32_e32 v162, 0xffff0000, v162
	v_mul_f32_e32 v127, v116, v127
	v_mul_f32_e32 v162, v117, v162
	v_cvt_pk_bf16_f32 v162, v127, v162
	v_lshlrev_b32_e32 v127, 16, v163
	v_and_b32_e32 v163, 0xffff0000, v163
	v_mul_f32_e32 v127, v118, v127
	v_mul_f32_e32 v163, v119, v163
	v_cvt_pk_bf16_f32 v163, v127, v163
	v_lshlrev_b32_e32 v127, 16, v164
	v_and_b32_e32 v164, 0xffff0000, v164
	v_mul_f32_e32 v127, v112, v127
	v_mul_f32_e32 v164, v113, v164
	v_cvt_pk_bf16_f32 v164, v127, v164
	v_lshlrev_b32_e32 v127, 16, v165
	v_and_b32_e32 v165, 0xffff0000, v165
	v_mul_f32_e32 v127, v114, v127
	v_mul_f32_e32 v165, v115, v165
	v_cvt_pk_bf16_f32 v165, v127, v165
	v_add_u32_e32 v126, 0x8000, v123
	global_store_dwordx4 v126, v[162:165], s[58:59]
	s_waitcnt vmcnt(15)
	v_add_f32_e32 v108, v108, v142
	v_add_f32_e32 v109, v109, v143
	v_add_f32_e32 v110, v110, v144
	v_add_f32_e32 v111, v111, v145
	v_add_f32_e32 v104, v104, v146
	v_add_f32_e32 v105, v105, v147
	v_add_f32_e32 v106, v106, v148
	v_add_f32_e32 v107, v107, v149
	v_mul_f32_e32 v108, 0xbfb8aa3b, v108
	v_mul_f32_e32 v109, 0xbfb8aa3b, v109
	v_mul_f32_e32 v110, 0xbfb8aa3b, v110
	v_mul_f32_e32 v111, 0xbfb8aa3b, v111
	v_mul_f32_e32 v104, 0xbfb8aa3b, v104
	v_mul_f32_e32 v105, 0xbfb8aa3b, v105
	v_mul_f32_e32 v106, 0xbfb8aa3b, v106
	v_mul_f32_e32 v107, 0xbfb8aa3b, v107
	v_exp_f32_e32 v108, v108
	v_exp_f32_e32 v109, v109
	v_exp_f32_e32 v110, v110
	v_exp_f32_e32 v111, v111
	v_exp_f32_e32 v104, v104
	v_exp_f32_e32 v105, v105
	v_exp_f32_e32 v106, v106
	v_exp_f32_e32 v107, v107
	v_add_f32_e32 v108, 1.0, v108
	v_add_f32_e32 v109, 1.0, v109
	v_add_f32_e32 v110, 1.0, v110
	v_add_f32_e32 v111, 1.0, v111
	v_add_f32_e32 v104, 1.0, v104
	v_add_f32_e32 v105, 1.0, v105
	v_add_f32_e32 v106, 1.0, v106
	v_add_f32_e32 v107, 1.0, v107
	v_rcp_f32_e32 v108, v108
	v_rcp_f32_e32 v109, v109
	v_rcp_f32_e32 v110, v110
	v_rcp_f32_e32 v111, v111
	v_rcp_f32_e32 v104, v104
	v_rcp_f32_e32 v105, v105
	v_rcp_f32_e32 v106, v106
	v_rcp_f32_e32 v107, v107
	v_lshlrev_b32_e32 v127, 16, v172
	v_and_b32_e32 v172, 0xffff0000, v172
	v_mul_f32_e32 v127, v108, v127
	v_mul_f32_e32 v172, v109, v172
	v_cvt_pk_bf16_f32 v172, v127, v172
	v_lshlrev_b32_e32 v127, 16, v173
	v_and_b32_e32 v173, 0xffff0000, v173
	v_mul_f32_e32 v127, v110, v127
	v_mul_f32_e32 v173, v111, v173
	v_cvt_pk_bf16_f32 v173, v127, v173
	v_lshlrev_b32_e32 v127, 16, v174
	v_and_b32_e32 v174, 0xffff0000, v174
	v_mul_f32_e32 v127, v104, v127
	v_mul_f32_e32 v174, v105, v174
	v_cvt_pk_bf16_f32 v174, v127, v174
	v_lshlrev_b32_e32 v127, 16, v175
	v_and_b32_e32 v175, 0xffff0000, v175
	v_mul_f32_e32 v127, v106, v127
	v_mul_f32_e32 v175, v107, v175
	v_cvt_pk_bf16_f32 v175, v127, v175
	v_add_u32_e32 v126, 0x10000, v123
	global_store_dwordx4 v126, v[172:175], s[58:59]
	s_waitcnt vmcnt(15)
	v_add_f32_e32 v100, v100, v142
	v_add_f32_e32 v101, v101, v143
	v_add_f32_e32 v102, v102, v144
	v_add_f32_e32 v103, v103, v145
	v_add_f32_e32 v96, v96, v146
	v_add_f32_e32 v97, v97, v147
	v_add_f32_e32 v98, v98, v148
	v_add_f32_e32 v99, v99, v149
	v_mul_f32_e32 v100, 0xbfb8aa3b, v100
	v_mul_f32_e32 v101, 0xbfb8aa3b, v101
	v_mul_f32_e32 v102, 0xbfb8aa3b, v102
	v_mul_f32_e32 v103, 0xbfb8aa3b, v103
	v_mul_f32_e32 v96, 0xbfb8aa3b, v96
	v_mul_f32_e32 v97, 0xbfb8aa3b, v97
	v_mul_f32_e32 v98, 0xbfb8aa3b, v98
	v_mul_f32_e32 v99, 0xbfb8aa3b, v99
	v_exp_f32_e32 v100, v100
	v_exp_f32_e32 v101, v101
	v_exp_f32_e32 v102, v102
	v_exp_f32_e32 v103, v103
	v_exp_f32_e32 v96, v96
	v_exp_f32_e32 v97, v97
	v_exp_f32_e32 v98, v98
	v_exp_f32_e32 v99, v99
	v_add_f32_e32 v100, 1.0, v100
	v_add_f32_e32 v101, 1.0, v101
	v_add_f32_e32 v102, 1.0, v102
	v_add_f32_e32 v103, 1.0, v103
	v_add_f32_e32 v96, 1.0, v96
	v_add_f32_e32 v97, 1.0, v97
	v_add_f32_e32 v98, 1.0, v98
	v_add_f32_e32 v99, 1.0, v99
	v_rcp_f32_e32 v100, v100
	v_rcp_f32_e32 v101, v101
	v_rcp_f32_e32 v102, v102
	v_rcp_f32_e32 v103, v103
	v_rcp_f32_e32 v96, v96
	v_rcp_f32_e32 v97, v97
	v_rcp_f32_e32 v98, v98
	v_rcp_f32_e32 v99, v99
	v_lshlrev_b32_e32 v127, 16, v176
	v_and_b32_e32 v176, 0xffff0000, v176
	v_mul_f32_e32 v127, v100, v127
	v_mul_f32_e32 v176, v101, v176
	v_cvt_pk_bf16_f32 v176, v127, v176
	v_lshlrev_b32_e32 v127, 16, v177
	v_and_b32_e32 v177, 0xffff0000, v177
	v_mul_f32_e32 v127, v102, v127
	v_mul_f32_e32 v177, v103, v177
	v_cvt_pk_bf16_f32 v177, v127, v177
	v_lshlrev_b32_e32 v127, 16, v178
	v_and_b32_e32 v178, 0xffff0000, v178
	v_mul_f32_e32 v127, v96, v127
	v_mul_f32_e32 v178, v97, v178
	v_cvt_pk_bf16_f32 v178, v127, v178
	v_lshlrev_b32_e32 v127, 16, v179
	v_and_b32_e32 v179, 0xffff0000, v179
	v_mul_f32_e32 v127, v98, v127
	v_mul_f32_e32 v179, v99, v179
	v_cvt_pk_bf16_f32 v179, v127, v179
	v_add_u32_e32 v126, 0x18000, v123
	global_store_dwordx4 v126, v[176:179], s[58:59]
	s_waitcnt vmcnt(15)
	v_add_f32_e32 v92, v92, v142
	v_add_f32_e32 v93, v93, v143
	v_add_f32_e32 v94, v94, v144
	v_add_f32_e32 v95, v95, v145
	v_add_f32_e32 v88, v88, v146
	v_add_f32_e32 v89, v89, v147
	v_add_f32_e32 v90, v90, v148
	v_add_f32_e32 v91, v91, v149
	v_mul_f32_e32 v92, 0xbfb8aa3b, v92
	v_mul_f32_e32 v93, 0xbfb8aa3b, v93
	v_mul_f32_e32 v94, 0xbfb8aa3b, v94
	v_mul_f32_e32 v95, 0xbfb8aa3b, v95
	v_mul_f32_e32 v88, 0xbfb8aa3b, v88
	v_mul_f32_e32 v89, 0xbfb8aa3b, v89
	v_mul_f32_e32 v90, 0xbfb8aa3b, v90
	v_mul_f32_e32 v91, 0xbfb8aa3b, v91
	v_exp_f32_e32 v92, v92
	v_exp_f32_e32 v93, v93
	v_exp_f32_e32 v94, v94
	v_exp_f32_e32 v95, v95
	v_exp_f32_e32 v88, v88
	v_exp_f32_e32 v89, v89
	v_exp_f32_e32 v90, v90
	v_exp_f32_e32 v91, v91
	v_add_f32_e32 v92, 1.0, v92
	v_add_f32_e32 v93, 1.0, v93
	v_add_f32_e32 v94, 1.0, v94
	v_add_f32_e32 v95, 1.0, v95
	v_add_f32_e32 v88, 1.0, v88
	v_add_f32_e32 v89, 1.0, v89
	v_add_f32_e32 v90, 1.0, v90
	v_add_f32_e32 v91, 1.0, v91
	v_rcp_f32_e32 v92, v92
	v_rcp_f32_e32 v93, v93
	v_rcp_f32_e32 v94, v94
	v_rcp_f32_e32 v95, v95
	v_rcp_f32_e32 v88, v88
	v_rcp_f32_e32 v89, v89
	v_rcp_f32_e32 v90, v90
	v_rcp_f32_e32 v91, v91
	v_lshlrev_b32_e32 v127, 16, v180
	v_and_b32_e32 v180, 0xffff0000, v180
	v_mul_f32_e32 v127, v92, v127
	v_mul_f32_e32 v180, v93, v180
	v_cvt_pk_bf16_f32 v180, v127, v180
	v_lshlrev_b32_e32 v127, 16, v181
	v_and_b32_e32 v181, 0xffff0000, v181
	v_mul_f32_e32 v127, v94, v127
	v_mul_f32_e32 v181, v95, v181
	v_cvt_pk_bf16_f32 v181, v127, v181
	v_lshlrev_b32_e32 v127, 16, v182
	v_and_b32_e32 v182, 0xffff0000, v182
	v_mul_f32_e32 v127, v88, v127
	v_mul_f32_e32 v182, v89, v182
	v_cvt_pk_bf16_f32 v182, v127, v182
	v_lshlrev_b32_e32 v127, 16, v183
	v_and_b32_e32 v183, 0xffff0000, v183
	v_mul_f32_e32 v127, v90, v127
	v_mul_f32_e32 v183, v91, v183
	v_cvt_pk_bf16_f32 v183, v127, v183
	v_add_u32_e32 v126, 0x40000, v123
	global_store_dwordx4 v126, v[180:183], s[58:59]
	s_waitcnt vmcnt(15)
	v_add_f32_e32 v84, v84, v142
	v_add_f32_e32 v85, v85, v143
	v_add_f32_e32 v86, v86, v144
	v_add_f32_e32 v87, v87, v145
	v_add_f32_e32 v80, v80, v146
	v_add_f32_e32 v81, v81, v147
	v_add_f32_e32 v82, v82, v148
	v_add_f32_e32 v83, v83, v149
	v_mul_f32_e32 v84, 0xbfb8aa3b, v84
	v_mul_f32_e32 v85, 0xbfb8aa3b, v85
	v_mul_f32_e32 v86, 0xbfb8aa3b, v86
	v_mul_f32_e32 v87, 0xbfb8aa3b, v87
	v_mul_f32_e32 v80, 0xbfb8aa3b, v80
	v_mul_f32_e32 v81, 0xbfb8aa3b, v81
	v_mul_f32_e32 v82, 0xbfb8aa3b, v82
	v_mul_f32_e32 v83, 0xbfb8aa3b, v83
	v_exp_f32_e32 v84, v84
	v_exp_f32_e32 v85, v85
	v_exp_f32_e32 v86, v86
	v_exp_f32_e32 v87, v87
	v_exp_f32_e32 v80, v80
	v_exp_f32_e32 v81, v81
	v_exp_f32_e32 v82, v82
	v_exp_f32_e32 v83, v83
	v_add_f32_e32 v84, 1.0, v84
	v_add_f32_e32 v85, 1.0, v85
	v_add_f32_e32 v86, 1.0, v86
	v_add_f32_e32 v87, 1.0, v87
	v_add_f32_e32 v80, 1.0, v80
	v_add_f32_e32 v81, 1.0, v81
	v_add_f32_e32 v82, 1.0, v82
	v_add_f32_e32 v83, 1.0, v83
	v_rcp_f32_e32 v84, v84
	v_rcp_f32_e32 v85, v85
	v_rcp_f32_e32 v86, v86
	v_rcp_f32_e32 v87, v87
	v_rcp_f32_e32 v80, v80
	v_rcp_f32_e32 v81, v81
	v_rcp_f32_e32 v82, v82
	v_rcp_f32_e32 v83, v83
	v_lshlrev_b32_e32 v127, 16, v184
	v_and_b32_e32 v184, 0xffff0000, v184
	v_mul_f32_e32 v127, v84, v127
	v_mul_f32_e32 v184, v85, v184
	v_cvt_pk_bf16_f32 v184, v127, v184
	v_lshlrev_b32_e32 v127, 16, v185
	v_and_b32_e32 v185, 0xffff0000, v185
	v_mul_f32_e32 v127, v86, v127
	v_mul_f32_e32 v185, v87, v185
	v_cvt_pk_bf16_f32 v185, v127, v185
	v_lshlrev_b32_e32 v127, 16, v186
	v_and_b32_e32 v186, 0xffff0000, v186
	v_mul_f32_e32 v127, v80, v127
	v_mul_f32_e32 v186, v81, v186
	v_cvt_pk_bf16_f32 v186, v127, v186
	v_lshlrev_b32_e32 v127, 16, v187
	v_and_b32_e32 v187, 0xffff0000, v187
	v_mul_f32_e32 v127, v82, v127
	v_mul_f32_e32 v187, v83, v187
	v_cvt_pk_bf16_f32 v187, v127, v187
	v_add_u32_e32 v126, 0x48000, v123
	global_store_dwordx4 v126, v[184:187], s[58:59]
	s_waitcnt vmcnt(15)
	v_add_f32_e32 v76, v76, v142
	v_add_f32_e32 v77, v77, v143
	v_add_f32_e32 v78, v78, v144
	v_add_f32_e32 v79, v79, v145
	v_add_f32_e32 v72, v72, v146
	v_add_f32_e32 v73, v73, v147
	v_add_f32_e32 v74, v74, v148
	v_add_f32_e32 v75, v75, v149
	v_mul_f32_e32 v76, 0xbfb8aa3b, v76
	v_mul_f32_e32 v77, 0xbfb8aa3b, v77
	v_mul_f32_e32 v78, 0xbfb8aa3b, v78
	v_mul_f32_e32 v79, 0xbfb8aa3b, v79
	v_mul_f32_e32 v72, 0xbfb8aa3b, v72
	v_mul_f32_e32 v73, 0xbfb8aa3b, v73
	v_mul_f32_e32 v74, 0xbfb8aa3b, v74
	v_mul_f32_e32 v75, 0xbfb8aa3b, v75
	v_exp_f32_e32 v76, v76
	v_exp_f32_e32 v77, v77
	v_exp_f32_e32 v78, v78
	v_exp_f32_e32 v79, v79
	v_exp_f32_e32 v72, v72
	v_exp_f32_e32 v73, v73
	v_exp_f32_e32 v74, v74
	v_exp_f32_e32 v75, v75
	v_add_f32_e32 v76, 1.0, v76
	v_add_f32_e32 v77, 1.0, v77
	v_add_f32_e32 v78, 1.0, v78
	v_add_f32_e32 v79, 1.0, v79
	v_add_f32_e32 v72, 1.0, v72
	v_add_f32_e32 v73, 1.0, v73
	v_add_f32_e32 v74, 1.0, v74
	v_add_f32_e32 v75, 1.0, v75
	v_rcp_f32_e32 v76, v76
	v_rcp_f32_e32 v77, v77
	v_rcp_f32_e32 v78, v78
	v_rcp_f32_e32 v79, v79
	v_rcp_f32_e32 v72, v72
	v_rcp_f32_e32 v73, v73
	v_rcp_f32_e32 v74, v74
	v_rcp_f32_e32 v75, v75
	v_lshlrev_b32_e32 v127, 16, v188
	v_and_b32_e32 v188, 0xffff0000, v188
	v_mul_f32_e32 v127, v76, v127
	v_mul_f32_e32 v188, v77, v188
	v_cvt_pk_bf16_f32 v188, v127, v188
	v_lshlrev_b32_e32 v127, 16, v189
	v_and_b32_e32 v189, 0xffff0000, v189
	v_mul_f32_e32 v127, v78, v127
	v_mul_f32_e32 v189, v79, v189
	v_cvt_pk_bf16_f32 v189, v127, v189
	v_lshlrev_b32_e32 v127, 16, v190
	v_and_b32_e32 v190, 0xffff0000, v190
	v_mul_f32_e32 v127, v72, v127
	v_mul_f32_e32 v190, v73, v190
	v_cvt_pk_bf16_f32 v190, v127, v190
	v_lshlrev_b32_e32 v127, 16, v191
	v_and_b32_e32 v191, 0xffff0000, v191
	v_mul_f32_e32 v127, v74, v127
	v_mul_f32_e32 v191, v75, v191
	v_cvt_pk_bf16_f32 v191, v127, v191
	v_add_u32_e32 v126, 0x50000, v123
	global_store_dwordx4 v126, v[188:191], s[58:59]
	s_waitcnt vmcnt(15)
	v_add_f32_e32 v68, v68, v142
	v_add_f32_e32 v69, v69, v143
	v_add_f32_e32 v70, v70, v144
	v_add_f32_e32 v71, v71, v145
	v_add_f32_e32 v64, v64, v146
	v_add_f32_e32 v65, v65, v147
	v_add_f32_e32 v66, v66, v148
	v_add_f32_e32 v67, v67, v149
	v_mul_f32_e32 v68, 0xbfb8aa3b, v68
	v_mul_f32_e32 v69, 0xbfb8aa3b, v69
	v_mul_f32_e32 v70, 0xbfb8aa3b, v70
	v_mul_f32_e32 v71, 0xbfb8aa3b, v71
	v_mul_f32_e32 v64, 0xbfb8aa3b, v64
	v_mul_f32_e32 v65, 0xbfb8aa3b, v65
	v_mul_f32_e32 v66, 0xbfb8aa3b, v66
	v_mul_f32_e32 v67, 0xbfb8aa3b, v67
	v_exp_f32_e32 v68, v68
	v_exp_f32_e32 v69, v69
	v_exp_f32_e32 v70, v70
	v_exp_f32_e32 v71, v71
	v_exp_f32_e32 v64, v64
	v_exp_f32_e32 v65, v65
	v_exp_f32_e32 v66, v66
	v_exp_f32_e32 v67, v67
	v_add_f32_e32 v68, 1.0, v68
	v_add_f32_e32 v69, 1.0, v69
	v_add_f32_e32 v70, 1.0, v70
	v_add_f32_e32 v71, 1.0, v71
	v_add_f32_e32 v64, 1.0, v64
	v_add_f32_e32 v65, 1.0, v65
	v_add_f32_e32 v66, 1.0, v66
	v_add_f32_e32 v67, 1.0, v67
	v_rcp_f32_e32 v68, v68
	v_rcp_f32_e32 v69, v69
	v_rcp_f32_e32 v70, v70
	v_rcp_f32_e32 v71, v71
	v_rcp_f32_e32 v64, v64
	v_rcp_f32_e32 v65, v65
	v_rcp_f32_e32 v66, v66
	v_rcp_f32_e32 v67, v67
	v_lshlrev_b32_e32 v127, 16, v192
	v_and_b32_e32 v192, 0xffff0000, v192
	v_mul_f32_e32 v127, v68, v127
	v_mul_f32_e32 v192, v69, v192
	v_cvt_pk_bf16_f32 v192, v127, v192
	v_lshlrev_b32_e32 v127, 16, v193
	v_and_b32_e32 v193, 0xffff0000, v193
	v_mul_f32_e32 v127, v70, v127
	v_mul_f32_e32 v193, v71, v193
	v_cvt_pk_bf16_f32 v193, v127, v193
	v_lshlrev_b32_e32 v127, 16, v194
	v_and_b32_e32 v194, 0xffff0000, v194
	v_mul_f32_e32 v127, v64, v127
	v_mul_f32_e32 v194, v65, v194
	v_cvt_pk_bf16_f32 v194, v127, v194
	v_lshlrev_b32_e32 v127, 16, v195
	v_and_b32_e32 v195, 0xffff0000, v195
	v_mul_f32_e32 v127, v66, v127
	v_mul_f32_e32 v195, v67, v195
	v_cvt_pk_bf16_f32 v195, v127, v195
	v_add_u32_e32 v126, 0x58000, v123
	global_store_dwordx4 v126, v[192:195], s[58:59]
	s_waitcnt vmcnt(15)
	v_add_f32_e32 v60, v60, v150
	v_add_f32_e32 v61, v61, v151
	v_add_f32_e32 v62, v62, v152
	v_add_f32_e32 v63, v63, v153
	v_add_f32_e32 v56, v56, v154
	v_add_f32_e32 v57, v57, v155
	v_add_f32_e32 v58, v58, v156
	v_add_f32_e32 v59, v59, v157
	v_mul_f32_e32 v60, 0xbfb8aa3b, v60
	v_mul_f32_e32 v61, 0xbfb8aa3b, v61
	v_mul_f32_e32 v62, 0xbfb8aa3b, v62
	v_mul_f32_e32 v63, 0xbfb8aa3b, v63
	v_mul_f32_e32 v56, 0xbfb8aa3b, v56
	v_mul_f32_e32 v57, 0xbfb8aa3b, v57
	v_mul_f32_e32 v58, 0xbfb8aa3b, v58
	v_mul_f32_e32 v59, 0xbfb8aa3b, v59
	v_exp_f32_e32 v60, v60
	v_exp_f32_e32 v61, v61
	v_exp_f32_e32 v62, v62
	v_exp_f32_e32 v63, v63
	v_exp_f32_e32 v56, v56
	v_exp_f32_e32 v57, v57
	v_exp_f32_e32 v58, v58
	v_exp_f32_e32 v59, v59
	v_add_f32_e32 v60, 1.0, v60
	v_add_f32_e32 v61, 1.0, v61
	v_add_f32_e32 v62, 1.0, v62
	v_add_f32_e32 v63, 1.0, v63
	v_add_f32_e32 v56, 1.0, v56
	v_add_f32_e32 v57, 1.0, v57
	v_add_f32_e32 v58, 1.0, v58
	v_add_f32_e32 v59, 1.0, v59
	v_rcp_f32_e32 v60, v60
	v_rcp_f32_e32 v61, v61
	v_rcp_f32_e32 v62, v62
	v_rcp_f32_e32 v63, v63
	v_rcp_f32_e32 v56, v56
	v_rcp_f32_e32 v57, v57
	v_rcp_f32_e32 v58, v58
	v_rcp_f32_e32 v59, v59
	v_lshlrev_b32_e32 v127, 16, v216
	v_and_b32_e32 v216, 0xffff0000, v216
	v_mul_f32_e32 v127, v60, v127
	v_mul_f32_e32 v216, v61, v216
	v_cvt_pk_bf16_f32 v216, v127, v216
	v_lshlrev_b32_e32 v127, 16, v217
	v_and_b32_e32 v217, 0xffff0000, v217
	v_mul_f32_e32 v127, v62, v127
	v_mul_f32_e32 v217, v63, v217
	v_cvt_pk_bf16_f32 v217, v127, v217
	v_lshlrev_b32_e32 v127, 16, v218
	v_and_b32_e32 v218, 0xffff0000, v218
	v_mul_f32_e32 v127, v56, v127
	v_mul_f32_e32 v218, v57, v218
	v_cvt_pk_bf16_f32 v218, v127, v218
	v_lshlrev_b32_e32 v127, 16, v219
	v_and_b32_e32 v219, 0xffff0000, v219
	v_mul_f32_e32 v127, v58, v127
	v_mul_f32_e32 v219, v59, v219
	v_cvt_pk_bf16_f32 v219, v127, v219
	global_store_dwordx4 v123, v[216:219], s[58:59] offset:256
	s_waitcnt vmcnt(15)
	v_add_f32_e32 v52, v52, v150
	v_add_f32_e32 v53, v53, v151
	v_add_f32_e32 v54, v54, v152
	v_add_f32_e32 v55, v55, v153
	v_add_f32_e32 v48, v48, v154
	v_add_f32_e32 v49, v49, v155
	v_add_f32_e32 v50, v50, v156
	v_add_f32_e32 v51, v51, v157
	v_mul_f32_e32 v52, 0xbfb8aa3b, v52
	v_mul_f32_e32 v53, 0xbfb8aa3b, v53
	v_mul_f32_e32 v54, 0xbfb8aa3b, v54
	v_mul_f32_e32 v55, 0xbfb8aa3b, v55
	v_mul_f32_e32 v48, 0xbfb8aa3b, v48
	v_mul_f32_e32 v49, 0xbfb8aa3b, v49
	v_mul_f32_e32 v50, 0xbfb8aa3b, v50
	v_mul_f32_e32 v51, 0xbfb8aa3b, v51
	v_exp_f32_e32 v52, v52
	v_exp_f32_e32 v53, v53
	v_exp_f32_e32 v54, v54
	v_exp_f32_e32 v55, v55
	v_exp_f32_e32 v48, v48
	v_exp_f32_e32 v49, v49
	v_exp_f32_e32 v50, v50
	v_exp_f32_e32 v51, v51
	v_add_f32_e32 v52, 1.0, v52
	v_add_f32_e32 v53, 1.0, v53
	v_add_f32_e32 v54, 1.0, v54
	v_add_f32_e32 v55, 1.0, v55
	v_add_f32_e32 v48, 1.0, v48
	v_add_f32_e32 v49, 1.0, v49
	v_add_f32_e32 v50, 1.0, v50
	v_add_f32_e32 v51, 1.0, v51
	v_rcp_f32_e32 v52, v52
	v_rcp_f32_e32 v53, v53
	v_rcp_f32_e32 v54, v54
	v_rcp_f32_e32 v55, v55
	v_rcp_f32_e32 v48, v48
	v_rcp_f32_e32 v49, v49
	v_rcp_f32_e32 v50, v50
	v_rcp_f32_e32 v51, v51
	v_lshlrev_b32_e32 v127, 16, v220
	v_and_b32_e32 v220, 0xffff0000, v220
	v_mul_f32_e32 v127, v52, v127
	v_mul_f32_e32 v220, v53, v220
	v_cvt_pk_bf16_f32 v220, v127, v220
	v_lshlrev_b32_e32 v127, 16, v221
	v_and_b32_e32 v221, 0xffff0000, v221
	v_mul_f32_e32 v127, v54, v127
	v_mul_f32_e32 v221, v55, v221
	v_cvt_pk_bf16_f32 v221, v127, v221
	v_lshlrev_b32_e32 v127, 16, v222
	v_and_b32_e32 v222, 0xffff0000, v222
	v_mul_f32_e32 v127, v48, v127
	v_mul_f32_e32 v222, v49, v222
	v_cvt_pk_bf16_f32 v222, v127, v222
	v_lshlrev_b32_e32 v127, 16, v223
	v_and_b32_e32 v223, 0xffff0000, v223
	v_mul_f32_e32 v127, v50, v127
	v_mul_f32_e32 v223, v51, v223
	v_cvt_pk_bf16_f32 v223, v127, v223
	v_add_u32_e32 v126, 0x8000, v123
	global_store_dwordx4 v126, v[220:223], s[58:59] offset:256
	s_waitcnt vmcnt(15)
	v_add_f32_e32 v44, v44, v150
	v_add_f32_e32 v45, v45, v151
	v_add_f32_e32 v46, v46, v152
	v_add_f32_e32 v47, v47, v153
	v_add_f32_e32 v40, v40, v154
	v_add_f32_e32 v41, v41, v155
	v_add_f32_e32 v42, v42, v156
	v_add_f32_e32 v43, v43, v157
	v_mul_f32_e32 v44, 0xbfb8aa3b, v44
	v_mul_f32_e32 v45, 0xbfb8aa3b, v45
	v_mul_f32_e32 v46, 0xbfb8aa3b, v46
	v_mul_f32_e32 v47, 0xbfb8aa3b, v47
	v_mul_f32_e32 v40, 0xbfb8aa3b, v40
	v_mul_f32_e32 v41, 0xbfb8aa3b, v41
	v_mul_f32_e32 v42, 0xbfb8aa3b, v42
	v_mul_f32_e32 v43, 0xbfb8aa3b, v43
	v_exp_f32_e32 v44, v44
	v_exp_f32_e32 v45, v45
	v_exp_f32_e32 v46, v46
	v_exp_f32_e32 v47, v47
	v_exp_f32_e32 v40, v40
	v_exp_f32_e32 v41, v41
	v_exp_f32_e32 v42, v42
	v_exp_f32_e32 v43, v43
	v_add_f32_e32 v44, 1.0, v44
	v_add_f32_e32 v45, 1.0, v45
	v_add_f32_e32 v46, 1.0, v46
	v_add_f32_e32 v47, 1.0, v47
	v_add_f32_e32 v40, 1.0, v40
	v_add_f32_e32 v41, 1.0, v41
	v_add_f32_e32 v42, 1.0, v42
	v_add_f32_e32 v43, 1.0, v43
	v_rcp_f32_e32 v44, v44
	v_rcp_f32_e32 v45, v45
	v_rcp_f32_e32 v46, v46
	v_rcp_f32_e32 v47, v47
	v_rcp_f32_e32 v40, v40
	v_rcp_f32_e32 v41, v41
	v_rcp_f32_e32 v42, v42
	v_rcp_f32_e32 v43, v43
	v_lshlrev_b32_e32 v127, 16, v224
	v_and_b32_e32 v224, 0xffff0000, v224
	v_mul_f32_e32 v127, v44, v127
	v_mul_f32_e32 v224, v45, v224
	v_cvt_pk_bf16_f32 v224, v127, v224
	v_lshlrev_b32_e32 v127, 16, v225
	v_and_b32_e32 v225, 0xffff0000, v225
	v_mul_f32_e32 v127, v46, v127
	v_mul_f32_e32 v225, v47, v225
	v_cvt_pk_bf16_f32 v225, v127, v225
	v_lshlrev_b32_e32 v127, 16, v226
	v_and_b32_e32 v226, 0xffff0000, v226
	v_mul_f32_e32 v127, v40, v127
	v_mul_f32_e32 v226, v41, v226
	v_cvt_pk_bf16_f32 v226, v127, v226
	v_lshlrev_b32_e32 v127, 16, v227
	v_and_b32_e32 v227, 0xffff0000, v227
	v_mul_f32_e32 v127, v42, v127
	v_mul_f32_e32 v227, v43, v227
	v_cvt_pk_bf16_f32 v227, v127, v227
	v_add_u32_e32 v126, 0x10000, v123
	global_store_dwordx4 v126, v[224:227], s[58:59] offset:256
	s_waitcnt vmcnt(15)
	v_add_f32_e32 v36, v36, v150
	v_add_f32_e32 v37, v37, v151
	v_add_f32_e32 v38, v38, v152
	v_add_f32_e32 v39, v39, v153
	v_add_f32_e32 v32, v32, v154
	v_add_f32_e32 v33, v33, v155
	v_add_f32_e32 v34, v34, v156
	v_add_f32_e32 v35, v35, v157
	v_mul_f32_e32 v36, 0xbfb8aa3b, v36
	v_mul_f32_e32 v37, 0xbfb8aa3b, v37
	v_mul_f32_e32 v38, 0xbfb8aa3b, v38
	v_mul_f32_e32 v39, 0xbfb8aa3b, v39
	v_mul_f32_e32 v32, 0xbfb8aa3b, v32
	v_mul_f32_e32 v33, 0xbfb8aa3b, v33
	v_mul_f32_e32 v34, 0xbfb8aa3b, v34
	v_mul_f32_e32 v35, 0xbfb8aa3b, v35
	v_exp_f32_e32 v36, v36
	v_exp_f32_e32 v37, v37
	v_exp_f32_e32 v38, v38
	v_exp_f32_e32 v39, v39
	v_exp_f32_e32 v32, v32
	v_exp_f32_e32 v33, v33
	v_exp_f32_e32 v34, v34
	v_exp_f32_e32 v35, v35
	v_add_f32_e32 v36, 1.0, v36
	v_add_f32_e32 v37, 1.0, v37
	v_add_f32_e32 v38, 1.0, v38
	v_add_f32_e32 v39, 1.0, v39
	v_add_f32_e32 v32, 1.0, v32
	v_add_f32_e32 v33, 1.0, v33
	v_add_f32_e32 v34, 1.0, v34
	v_add_f32_e32 v35, 1.0, v35
	v_rcp_f32_e32 v36, v36
	v_rcp_f32_e32 v37, v37
	v_rcp_f32_e32 v38, v38
	v_rcp_f32_e32 v39, v39
	v_rcp_f32_e32 v32, v32
	v_rcp_f32_e32 v33, v33
	v_rcp_f32_e32 v34, v34
	v_rcp_f32_e32 v35, v35
	v_lshlrev_b32_e32 v127, 16, v228
	v_and_b32_e32 v228, 0xffff0000, v228
	v_mul_f32_e32 v127, v36, v127
	v_mul_f32_e32 v228, v37, v228
	v_cvt_pk_bf16_f32 v228, v127, v228
	v_lshlrev_b32_e32 v127, 16, v229
	v_and_b32_e32 v229, 0xffff0000, v229
	v_mul_f32_e32 v127, v38, v127
	v_mul_f32_e32 v229, v39, v229
	v_cvt_pk_bf16_f32 v229, v127, v229
	v_lshlrev_b32_e32 v127, 16, v230
	v_and_b32_e32 v230, 0xffff0000, v230
	v_mul_f32_e32 v127, v32, v127
	v_mul_f32_e32 v230, v33, v230
	v_cvt_pk_bf16_f32 v230, v127, v230
	v_lshlrev_b32_e32 v127, 16, v231
	v_and_b32_e32 v231, 0xffff0000, v231
	v_mul_f32_e32 v127, v34, v127
	v_mul_f32_e32 v231, v35, v231
	v_cvt_pk_bf16_f32 v231, v127, v231
	v_add_u32_e32 v126, 0x18000, v123
	global_store_dwordx4 v126, v[228:231], s[58:59] offset:256
	s_waitcnt vmcnt(15)
	v_add_f32_e32 v28, v28, v150
	v_add_f32_e32 v29, v29, v151
	v_add_f32_e32 v30, v30, v152
	v_add_f32_e32 v31, v31, v153
	v_add_f32_e32 v24, v24, v154
	v_add_f32_e32 v25, v25, v155
	v_add_f32_e32 v26, v26, v156
	v_add_f32_e32 v27, v27, v157
	v_mul_f32_e32 v28, 0xbfb8aa3b, v28
	v_mul_f32_e32 v29, 0xbfb8aa3b, v29
	v_mul_f32_e32 v30, 0xbfb8aa3b, v30
	v_mul_f32_e32 v31, 0xbfb8aa3b, v31
	v_mul_f32_e32 v24, 0xbfb8aa3b, v24
	v_mul_f32_e32 v25, 0xbfb8aa3b, v25
	v_mul_f32_e32 v26, 0xbfb8aa3b, v26
	v_mul_f32_e32 v27, 0xbfb8aa3b, v27
	v_exp_f32_e32 v28, v28
	v_exp_f32_e32 v29, v29
	v_exp_f32_e32 v30, v30
	v_exp_f32_e32 v31, v31
	v_exp_f32_e32 v24, v24
	v_exp_f32_e32 v25, v25
	v_exp_f32_e32 v26, v26
	v_exp_f32_e32 v27, v27
	v_add_f32_e32 v28, 1.0, v28
	v_add_f32_e32 v29, 1.0, v29
	v_add_f32_e32 v30, 1.0, v30
	v_add_f32_e32 v31, 1.0, v31
	v_add_f32_e32 v24, 1.0, v24
	v_add_f32_e32 v25, 1.0, v25
	v_add_f32_e32 v26, 1.0, v26
	v_add_f32_e32 v27, 1.0, v27
	v_rcp_f32_e32 v28, v28
	v_rcp_f32_e32 v29, v29
	v_rcp_f32_e32 v30, v30
	v_rcp_f32_e32 v31, v31
	v_rcp_f32_e32 v24, v24
	v_rcp_f32_e32 v25, v25
	v_rcp_f32_e32 v26, v26
	v_rcp_f32_e32 v27, v27
	v_lshlrev_b32_e32 v127, 16, v236
	v_and_b32_e32 v236, 0xffff0000, v236
	v_mul_f32_e32 v127, v28, v127
	v_mul_f32_e32 v236, v29, v236
	v_cvt_pk_bf16_f32 v236, v127, v236
	v_lshlrev_b32_e32 v127, 16, v237
	v_and_b32_e32 v237, 0xffff0000, v237
	v_mul_f32_e32 v127, v30, v127
	v_mul_f32_e32 v237, v31, v237
	v_cvt_pk_bf16_f32 v237, v127, v237
	v_lshlrev_b32_e32 v127, 16, v238
	v_and_b32_e32 v238, 0xffff0000, v238
	v_mul_f32_e32 v127, v24, v127
	v_mul_f32_e32 v238, v25, v238
	v_cvt_pk_bf16_f32 v238, v127, v238
	v_lshlrev_b32_e32 v127, 16, v239
	v_and_b32_e32 v239, 0xffff0000, v239
	v_mul_f32_e32 v127, v26, v127
	v_mul_f32_e32 v239, v27, v239
	v_cvt_pk_bf16_f32 v239, v127, v239
	v_add_u32_e32 v126, 0x40000, v123
	global_store_dwordx4 v126, v[236:239], s[58:59] offset:256
	s_waitcnt vmcnt(15)
	v_add_f32_e32 v20, v20, v150
	v_add_f32_e32 v21, v21, v151
	v_add_f32_e32 v22, v22, v152
	v_add_f32_e32 v23, v23, v153
	v_add_f32_e32 v16, v16, v154
	v_add_f32_e32 v17, v17, v155
	v_add_f32_e32 v18, v18, v156
	v_add_f32_e32 v19, v19, v157
	v_mul_f32_e32 v20, 0xbfb8aa3b, v20
	v_mul_f32_e32 v21, 0xbfb8aa3b, v21
	v_mul_f32_e32 v22, 0xbfb8aa3b, v22
	v_mul_f32_e32 v23, 0xbfb8aa3b, v23
	v_mul_f32_e32 v16, 0xbfb8aa3b, v16
	v_mul_f32_e32 v17, 0xbfb8aa3b, v17
	v_mul_f32_e32 v18, 0xbfb8aa3b, v18
	v_mul_f32_e32 v19, 0xbfb8aa3b, v19
	v_exp_f32_e32 v20, v20
	v_exp_f32_e32 v21, v21
	v_exp_f32_e32 v22, v22
	v_exp_f32_e32 v23, v23
	v_exp_f32_e32 v16, v16
	v_exp_f32_e32 v17, v17
	v_exp_f32_e32 v18, v18
	v_exp_f32_e32 v19, v19
	v_add_f32_e32 v20, 1.0, v20
	v_add_f32_e32 v21, 1.0, v21
	v_add_f32_e32 v22, 1.0, v22
	v_add_f32_e32 v23, 1.0, v23
	v_add_f32_e32 v16, 1.0, v16
	v_add_f32_e32 v17, 1.0, v17
	v_add_f32_e32 v18, 1.0, v18
	v_add_f32_e32 v19, 1.0, v19
	v_rcp_f32_e32 v20, v20
	v_rcp_f32_e32 v21, v21
	v_rcp_f32_e32 v22, v22
	v_rcp_f32_e32 v23, v23
	v_rcp_f32_e32 v16, v16
	v_rcp_f32_e32 v17, v17
	v_rcp_f32_e32 v18, v18
	v_rcp_f32_e32 v19, v19
	v_lshlrev_b32_e32 v127, 16, v240
	v_and_b32_e32 v240, 0xffff0000, v240
	v_mul_f32_e32 v127, v20, v127
	v_mul_f32_e32 v240, v21, v240
	v_cvt_pk_bf16_f32 v240, v127, v240
	v_lshlrev_b32_e32 v127, 16, v241
	v_and_b32_e32 v241, 0xffff0000, v241
	v_mul_f32_e32 v127, v22, v127
	v_mul_f32_e32 v241, v23, v241
	v_cvt_pk_bf16_f32 v241, v127, v241
	v_lshlrev_b32_e32 v127, 16, v242
	v_and_b32_e32 v242, 0xffff0000, v242
	v_mul_f32_e32 v127, v16, v127
	v_mul_f32_e32 v242, v17, v242
	v_cvt_pk_bf16_f32 v242, v127, v242
	v_lshlrev_b32_e32 v127, 16, v243
	v_and_b32_e32 v243, 0xffff0000, v243
	v_mul_f32_e32 v127, v18, v127
	v_mul_f32_e32 v243, v19, v243
	v_cvt_pk_bf16_f32 v243, v127, v243
	v_add_u32_e32 v126, 0x48000, v123
	global_store_dwordx4 v126, v[240:243], s[58:59] offset:256
	s_waitcnt vmcnt(15)
	v_add_f32_e32 v12, v12, v150
	v_add_f32_e32 v13, v13, v151
	v_add_f32_e32 v14, v14, v152
	v_add_f32_e32 v15, v15, v153
	v_add_f32_e32 v8, v8, v154
	v_add_f32_e32 v9, v9, v155
	v_add_f32_e32 v10, v10, v156
	v_add_f32_e32 v11, v11, v157
	v_mul_f32_e32 v12, 0xbfb8aa3b, v12
	v_mul_f32_e32 v13, 0xbfb8aa3b, v13
	v_mul_f32_e32 v14, 0xbfb8aa3b, v14
	v_mul_f32_e32 v15, 0xbfb8aa3b, v15
	v_mul_f32_e32 v8, 0xbfb8aa3b, v8
	v_mul_f32_e32 v9, 0xbfb8aa3b, v9
	v_mul_f32_e32 v10, 0xbfb8aa3b, v10
	v_mul_f32_e32 v11, 0xbfb8aa3b, v11
	v_exp_f32_e32 v12, v12
	v_exp_f32_e32 v13, v13
	v_exp_f32_e32 v14, v14
	v_exp_f32_e32 v15, v15
	v_exp_f32_e32 v8, v8
	v_exp_f32_e32 v9, v9
	v_exp_f32_e32 v10, v10
	v_exp_f32_e32 v11, v11
	v_add_f32_e32 v12, 1.0, v12
	v_add_f32_e32 v13, 1.0, v13
	v_add_f32_e32 v14, 1.0, v14
	v_add_f32_e32 v15, 1.0, v15
	v_add_f32_e32 v8, 1.0, v8
	v_add_f32_e32 v9, 1.0, v9
	v_add_f32_e32 v10, 1.0, v10
	v_add_f32_e32 v11, 1.0, v11
	v_rcp_f32_e32 v12, v12
	v_rcp_f32_e32 v13, v13
	v_rcp_f32_e32 v14, v14
	v_rcp_f32_e32 v15, v15
	v_rcp_f32_e32 v8, v8
	v_rcp_f32_e32 v9, v9
	v_rcp_f32_e32 v10, v10
	v_rcp_f32_e32 v11, v11
	v_lshlrev_b32_e32 v127, 16, v244
	v_and_b32_e32 v244, 0xffff0000, v244
	v_mul_f32_e32 v127, v12, v127
	v_mul_f32_e32 v244, v13, v244
	v_cvt_pk_bf16_f32 v244, v127, v244
	v_lshlrev_b32_e32 v127, 16, v245
	v_and_b32_e32 v245, 0xffff0000, v245
	v_mul_f32_e32 v127, v14, v127
	v_mul_f32_e32 v245, v15, v245
	v_cvt_pk_bf16_f32 v245, v127, v245
	v_lshlrev_b32_e32 v127, 16, v246
	v_and_b32_e32 v246, 0xffff0000, v246
	v_mul_f32_e32 v127, v8, v127
	v_mul_f32_e32 v246, v9, v246
	v_cvt_pk_bf16_f32 v246, v127, v246
	v_lshlrev_b32_e32 v127, 16, v247
	v_and_b32_e32 v247, 0xffff0000, v247
	v_mul_f32_e32 v127, v10, v127
	v_mul_f32_e32 v247, v11, v247
	v_cvt_pk_bf16_f32 v247, v127, v247
	v_add_u32_e32 v126, 0x50000, v123
	global_store_dwordx4 v126, v[244:247], s[58:59] offset:256
	s_waitcnt vmcnt(15)
	v_add_f32_e32 v4, v4, v150
	v_add_f32_e32 v5, v5, v151
	v_add_f32_e32 v6, v6, v152
	v_add_f32_e32 v7, v7, v153
	v_add_f32_e32 v0, v0, v154
	v_add_f32_e32 v1, v1, v155
	v_add_f32_e32 v2, v2, v156
	v_add_f32_e32 v3, v3, v157
	v_mul_f32_e32 v4, 0xbfb8aa3b, v4
	v_mul_f32_e32 v5, 0xbfb8aa3b, v5
	v_mul_f32_e32 v6, 0xbfb8aa3b, v6
	v_mul_f32_e32 v7, 0xbfb8aa3b, v7
	v_mul_f32_e32 v0, 0xbfb8aa3b, v0
	v_mul_f32_e32 v1, 0xbfb8aa3b, v1
	v_mul_f32_e32 v2, 0xbfb8aa3b, v2
	v_mul_f32_e32 v3, 0xbfb8aa3b, v3
	v_exp_f32_e32 v4, v4
	v_exp_f32_e32 v5, v5
	v_exp_f32_e32 v6, v6
	v_exp_f32_e32 v7, v7
	v_exp_f32_e32 v0, v0
	v_exp_f32_e32 v1, v1
	v_exp_f32_e32 v2, v2
	v_exp_f32_e32 v3, v3
	v_add_f32_e32 v4, 1.0, v4
	v_add_f32_e32 v5, 1.0, v5
	v_add_f32_e32 v6, 1.0, v6
	v_add_f32_e32 v7, 1.0, v7
	v_add_f32_e32 v0, 1.0, v0
	v_add_f32_e32 v1, 1.0, v1
	v_add_f32_e32 v2, 1.0, v2
	v_add_f32_e32 v3, 1.0, v3
	v_rcp_f32_e32 v4, v4
	v_rcp_f32_e32 v5, v5
	v_rcp_f32_e32 v6, v6
	v_rcp_f32_e32 v7, v7
	v_rcp_f32_e32 v0, v0
	v_rcp_f32_e32 v1, v1
	v_rcp_f32_e32 v2, v2
	v_rcp_f32_e32 v3, v3
	v_lshlrev_b32_e32 v127, 16, v248
	v_and_b32_e32 v248, 0xffff0000, v248
	v_mul_f32_e32 v127, v4, v127
	v_mul_f32_e32 v248, v5, v248
	v_cvt_pk_bf16_f32 v248, v127, v248
	v_lshlrev_b32_e32 v127, 16, v249
	v_and_b32_e32 v249, 0xffff0000, v249
	v_mul_f32_e32 v127, v6, v127
	v_mul_f32_e32 v249, v7, v249
	v_cvt_pk_bf16_f32 v249, v127, v249
	v_lshlrev_b32_e32 v127, 16, v250
	v_and_b32_e32 v250, 0xffff0000, v250
	v_mul_f32_e32 v127, v0, v127
	v_mul_f32_e32 v250, v1, v250
	v_cvt_pk_bf16_f32 v250, v127, v250
	v_lshlrev_b32_e32 v127, 16, v251
	v_and_b32_e32 v251, 0xffff0000, v251
	v_mul_f32_e32 v127, v2, v127
	v_mul_f32_e32 v251, v3, v251
	v_cvt_pk_bf16_f32 v251, v127, v251
	v_add_u32_e32 v126, 0x58000, v123
	global_store_dwordx4 v126, v[248:251], s[58:59] offset:256

.LBB0_479:
	v_lshl_add_u32 v8, s30, 9, v170
	s_mov_b32 s0, 0x80000
	v_cmp_gt_i32_e32 vcc, s0, v8
	s_and_saveexec_b64 s[38:39], vcc
	s_cbranch_execz .LBB0_482
	s_add_u32 s40, s50, 0x12300000
	s_addc_u32 s41, s51, 0
	s_lshl_b32 s0, s31, 9
	v_lshlrev_b32_e32 v9, 3, v8
	s_lshl_b32 s1, s31, 12
	s_mov_b64 s[42:43], 0
	s_add_u32 s44, s50, 0x6a01600
	s_addc_u32 s45, s51, 0
	v_ashrrev_i32_e32 v114, 5, v8
	v_lshlrev_b32_e32 v115, 9, v114
	v_and_b32_e32 v115, 0xffe00, v115
	v_and_b32_e32 v116, 31, v8
	v_lshlrev_b32_e32 v116, 4, v116
	v_add_u32_e32 v115, v115, v116
	v_ashrrev_i32_e32 v117, 14, v8
	v_and_b32_e32 v117, -8, v117
	v_lshl_add_u32 v115, v117, 20, v115
	v_mul_u32_u24_e32 v110, 0x1800, v114
	v_add_u32_e32 v110, v110, v116
	v_and_b32_e32 v117, 0x10000, v8
	v_cmp_eq_u32_e32 vcc, 0, v117
	s_nop 1
	v_cndmask_b32_e64 v111, -1.0, 1.0, vcc
	global_load_dwordx4 v[30:33], v115, s[40:41] nt
	v_add_u32_e32 v118, 0x100000, v115
	global_load_dwordx4 v[34:37], v118, s[40:41] nt
	v_add_u32_e32 v118, 0x200000, v115
	global_load_dwordx4 v[38:41], v118, s[40:41] nt
	v_add_u32_e32 v118, 0x300000, v115
	global_load_dwordx4 v[42:45], v118, s[40:41] nt
	v_add_u32_e32 v118, 0x400000, v115
	global_load_dwordx4 v[46:49], v118, s[40:41] nt
	v_add_u32_e32 v118, 0x500000, v115
	global_load_dwordx4 v[50:53], v118, s[40:41] nt
	v_add_u32_e32 v118, 0x600000, v115
	global_load_dwordx4 v[54:57], v118, s[40:41] nt
	v_add_u32_e32 v118, 0x700000, v115
	global_load_dwordx4 v[58:61], v118, s[40:41] nt
	global_load_dwordx4 v[62:65], v110, s[44:45]
.Ldftc_loop:
	v_add_u32_e32 v8, s0, v8
	s_nop 0
	v_readfirstlane_b32 s2, v8
	s_cmp_gt_i32 s2, s21
	s_cbranch_scc1 .Ldftc_last0
	v_ashrrev_i32_e32 v114, 5, v8
	v_lshlrev_b32_e32 v115, 9, v114
	v_and_b32_e32 v115, 0xffe00, v115
	v_and_b32_e32 v116, 31, v8
	v_lshlrev_b32_e32 v116, 4, v116
	v_add_u32_e32 v115, v115, v116
	v_ashrrev_i32_e32 v117, 14, v8
	v_and_b32_e32 v117, -8, v117
	v_lshl_add_u32 v115, v117, 20, v115
	v_mul_u32_u24_e32 v112, 0x1800, v114
	v_add_u32_e32 v112, v112, v116
	v_and_b32_e32 v117, 0x10000, v8
	v_cmp_eq_u32_e32 vcc, 0, v117
	s_nop 1
	v_cndmask_b32_e64 v113, -1.0, 1.0, vcc
	global_load_dwordx4 v[66:69], v115, s[40:41] nt
	v_add_u32_e32 v118, 0x100000, v115
	global_load_dwordx4 v[70:73], v118, s[40:41] nt
	v_add_u32_e32 v118, 0x200000, v115
	global_load_dwordx4 v[74:77], v118, s[40:41] nt
	v_add_u32_e32 v118, 0x300000, v115
	global_load_dwordx4 v[78:81], v118, s[40:41] nt
	v_add_u32_e32 v118, 0x400000, v115
	global_load_dwordx4 v[82:85], v118, s[40:41] nt
	v_add_u32_e32 v118, 0x500000, v115
	global_load_dwordx4 v[86:89], v118, s[40:41] nt
	v_add_u32_e32 v118, 0x600000, v115
	global_load_dwordx4 v[90:93], v118, s[40:41] nt
	v_add_u32_e32 v118, 0x700000, v115
	global_load_dwordx4 v[94:97], v118, s[40:41] nt
	global_load_dwordx4 v[98:101], v112, s[44:45]
	s_waitcnt vmcnt(9)
	v_lshlrev_b32_e32 v118, 16, v30
	v_and_b32_e32 v119, 0xffff0000, v30
	v_add_f32_e32 v120, 0, v118
	v_add_f32_e32 v121, 0, v119
	v_lshlrev_b32_e32 v118, 16, v31
	v_and_b32_e32 v119, 0xffff0000, v31
	v_add_f32_e32 v122, 0, v118
	v_add_f32_e32 v123, 0, v119
	v_lshlrev_b32_e32 v118, 16, v32
	v_and_b32_e32 v119, 0xffff0000, v32
	v_add_f32_e32 v124, 0, v118
	v_add_f32_e32 v125, 0, v119
	v_lshlrev_b32_e32 v118, 16, v33
	v_and_b32_e32 v119, 0xffff0000, v33
	v_add_f32_e32 v126, 0, v118
	v_add_f32_e32 v127, 0, v119
	v_lshlrev_b32_e32 v118, 16, v34
	v_and_b32_e32 v119, 0xffff0000, v34
	v_fma_f32 v120, v111, v118, v120
	v_fma_f32 v121, v111, v119, v121
	v_lshlrev_b32_e32 v118, 16, v35
	v_and_b32_e32 v119, 0xffff0000, v35
	v_fma_f32 v122, v111, v118, v122
	v_fma_f32 v123, v111, v119, v123
	v_lshlrev_b32_e32 v118, 16, v36
	v_and_b32_e32 v119, 0xffff0000, v36
	v_fma_f32 v124, v111, v118, v124
	v_fma_f32 v125, v111, v119, v125
	v_lshlrev_b32_e32 v118, 16, v37
	v_and_b32_e32 v119, 0xffff0000, v37
	v_fma_f32 v126, v111, v118, v126
	v_fma_f32 v127, v111, v119, v127
	v_lshlrev_b32_e32 v118, 16, v38
	v_and_b32_e32 v119, 0xffff0000, v38
	v_add_f32_e32 v120, v120, v118
	v_add_f32_e32 v121, v121, v119
	v_lshlrev_b32_e32 v118, 16, v39
	v_and_b32_e32 v119, 0xffff0000, v39
	v_add_f32_e32 v122, v122, v118
	v_add_f32_e32 v123, v123, v119
	v_lshlrev_b32_e32 v118, 16, v40
	v_and_b32_e32 v119, 0xffff0000, v40
	v_add_f32_e32 v124, v124, v118
	v_add_f32_e32 v125, v125, v119
	v_lshlrev_b32_e32 v118, 16, v41
	v_and_b32_e32 v119, 0xffff0000, v41
	v_add_f32_e32 v126, v126, v118
	v_add_f32_e32 v127, v127, v119
	v_lshlrev_b32_e32 v118, 16, v42
	v_and_b32_e32 v119, 0xffff0000, v42
	v_fma_f32 v120, v111, v118, v120
	v_fma_f32 v121, v111, v119, v121
	v_lshlrev_b32_e32 v118, 16, v43
	v_and_b32_e32 v119, 0xffff0000, v43
	v_fma_f32 v122, v111, v118, v122
	v_fma_f32 v123, v111, v119, v123
	v_lshlrev_b32_e32 v118, 16, v44
	v_and_b32_e32 v119, 0xffff0000, v44
	v_fma_f32 v124, v111, v118, v124
	v_fma_f32 v125, v111, v119, v125
	v_lshlrev_b32_e32 v118, 16, v45
	v_and_b32_e32 v119, 0xffff0000, v45
	v_fma_f32 v126, v111, v118, v126
	v_fma_f32 v127, v111, v119, v127
	v_lshlrev_b32_e32 v118, 16, v46
	v_and_b32_e32 v119, 0xffff0000, v46
	v_add_f32_e32 v120, v120, v118
	v_add_f32_e32 v121, v121, v119
	v_lshlrev_b32_e32 v118, 16, v47
	v_and_b32_e32 v119, 0xffff0000, v47
	v_add_f32_e32 v122, v122, v118
	v_add_f32_e32 v123, v123, v119
	v_lshlrev_b32_e32 v118, 16, v48
	v_and_b32_e32 v119, 0xffff0000, v48
	v_add_f32_e32 v124, v124, v118
	v_add_f32_e32 v125, v125, v119
	v_lshlrev_b32_e32 v118, 16, v49
	v_and_b32_e32 v119, 0xffff0000, v49
	v_add_f32_e32 v126, v126, v118
	v_add_f32_e32 v127, v127, v119
	v_lshlrev_b32_e32 v118, 16, v50
	v_and_b32_e32 v119, 0xffff0000, v50
	v_fma_f32 v120, v111, v118, v120
	v_fma_f32 v121, v111, v119, v121
	v_lshlrev_b32_e32 v118, 16, v51
	v_and_b32_e32 v119, 0xffff0000, v51
	v_fma_f32 v122, v111, v118, v122
	v_fma_f32 v123, v111, v119, v123
	v_lshlrev_b32_e32 v118, 16, v52
	v_and_b32_e32 v119, 0xffff0000, v52
	v_fma_f32 v124, v111, v118, v124
	v_fma_f32 v125, v111, v119, v125
	v_lshlrev_b32_e32 v118, 16, v53
	v_and_b32_e32 v119, 0xffff0000, v53
	v_fma_f32 v126, v111, v118, v126
	v_fma_f32 v127, v111, v119, v127
	v_lshlrev_b32_e32 v118, 16, v54
	v_and_b32_e32 v119, 0xffff0000, v54
	v_add_f32_e32 v120, v120, v118
	v_add_f32_e32 v121, v121, v119
	v_lshlrev_b32_e32 v118, 16, v55
	v_and_b32_e32 v119, 0xffff0000, v55
	v_add_f32_e32 v122, v122, v118
	v_add_f32_e32 v123, v123, v119
	v_lshlrev_b32_e32 v118, 16, v56
	v_and_b32_e32 v119, 0xffff0000, v56
	v_add_f32_e32 v124, v124, v118
	v_add_f32_e32 v125, v125, v119
	v_lshlrev_b32_e32 v118, 16, v57
	v_and_b32_e32 v119, 0xffff0000, v57
	v_add_f32_e32 v126, v126, v118
	v_add_f32_e32 v127, v127, v119
	v_lshlrev_b32_e32 v118, 16, v58
	v_and_b32_e32 v119, 0xffff0000, v58
	v_fma_f32 v120, v111, v118, v120
	v_fma_f32 v121, v111, v119, v121
	v_lshlrev_b32_e32 v118, 16, v59
	v_and_b32_e32 v119, 0xffff0000, v59
	v_fma_f32 v122, v111, v118, v122
	v_fma_f32 v123, v111, v119, v123
	v_lshlrev_b32_e32 v118, 16, v60
	v_and_b32_e32 v119, 0xffff0000, v60
	v_fma_f32 v124, v111, v118, v124
	v_fma_f32 v125, v111, v119, v125
	v_lshlrev_b32_e32 v118, 16, v61
	v_and_b32_e32 v119, 0xffff0000, v61
	v_fma_f32 v126, v111, v118, v126
	v_fma_f32 v127, v111, v119, v127
	v_lshlrev_b32_e32 v118, 16, v62
	v_and_b32_e32 v119, 0xffff0000, v62
	v_mul_f32_e32 v120, v120, v118
	v_mul_f32_e32 v121, v121, v119
	v_cvt_pk_bf16_f32 v62, v120, v121
	v_lshlrev_b32_e32 v118, 16, v63
	v_and_b32_e32 v119, 0xffff0000, v63
	v_mul_f32_e32 v122, v122, v118
	v_mul_f32_e32 v123, v123, v119
	v_cvt_pk_bf16_f32 v63, v122, v123
	v_lshlrev_b32_e32 v118, 16, v64
	v_and_b32_e32 v119, 0xffff0000, v64
	v_mul_f32_e32 v124, v124, v118
	v_mul_f32_e32 v125, v125, v119
	v_cvt_pk_bf16_f32 v64, v124, v125
	v_lshlrev_b32_e32 v118, 16, v65
	v_and_b32_e32 v119, 0xffff0000, v65
	v_mul_f32_e32 v126, v126, v118
	v_mul_f32_e32 v127, v127, v119
	v_cvt_pk_bf16_f32 v65, v126, v127
	global_store_dwordx4 v110, v[62:65], s[44:45]
	v_add_u32_e32 v8, s0, v8
	s_nop 0
	v_readfirstlane_b32 s2, v8
	s_cmp_gt_i32 s2, s21
	s_cbranch_scc1 .Ldftc_last1
	v_ashrrev_i32_e32 v114, 5, v8
	v_lshlrev_b32_e32 v115, 9, v114
	v_and_b32_e32 v115, 0xffe00, v115
	v_and_b32_e32 v116, 31, v8
	v_lshlrev_b32_e32 v116, 4, v116
	v_add_u32_e32 v115, v115, v116
	v_ashrrev_i32_e32 v117, 14, v8
	v_and_b32_e32 v117, -8, v117
	v_lshl_add_u32 v115, v117, 20, v115
	v_mul_u32_u24_e32 v110, 0x1800, v114
	v_add_u32_e32 v110, v110, v116
	v_and_b32_e32 v117, 0x10000, v8
	v_cmp_eq_u32_e32 vcc, 0, v117
	s_nop 1
	v_cndmask_b32_e64 v111, -1.0, 1.0, vcc
	global_load_dwordx4 v[30:33], v115, s[40:41] nt
	v_add_u32_e32 v118, 0x100000, v115
	global_load_dwordx4 v[34:37], v118, s[40:41] nt
	v_add_u32_e32 v118, 0x200000, v115
	global_load_dwordx4 v[38:41], v118, s[40:41] nt
	v_add_u32_e32 v118, 0x300000, v115
	global_load_dwordx4 v[42:45], v118, s[40:41] nt
	v_add_u32_e32 v118, 0x400000, v115
	global_load_dwordx4 v[46:49], v118, s[40:41] nt
	v_add_u32_e32 v118, 0x500000, v115
	global_load_dwordx4 v[50:53], v118, s[40:41] nt
	v_add_u32_e32 v118, 0x600000, v115
	global_load_dwordx4 v[54:57], v118, s[40:41] nt
	v_add_u32_e32 v118, 0x700000, v115
	global_load_dwordx4 v[58:61], v118, s[40:41] nt
	global_load_dwordx4 v[62:65], v110, s[44:45]
	s_waitcnt vmcnt(10)
	v_lshlrev_b32_e32 v118, 16, v66
	v_and_b32_e32 v119, 0xffff0000, v66
	v_add_f32_e32 v120, 0, v118
	v_add_f32_e32 v121, 0, v119
	v_lshlrev_b32_e32 v118, 16, v67
	v_and_b32_e32 v119, 0xffff0000, v67
	v_add_f32_e32 v122, 0, v118
	v_add_f32_e32 v123, 0, v119
	v_lshlrev_b32_e32 v118, 16, v68
	v_and_b32_e32 v119, 0xffff0000, v68
	v_add_f32_e32 v124, 0, v118
	v_add_f32_e32 v125, 0, v119
	v_lshlrev_b32_e32 v118, 16, v69
	v_and_b32_e32 v119, 0xffff0000, v69
	v_add_f32_e32 v126, 0, v118
	v_add_f32_e32 v127, 0, v119
	v_lshlrev_b32_e32 v118, 16, v70
	v_and_b32_e32 v119, 0xffff0000, v70
	v_fma_f32 v120, v113, v118, v120
	v_fma_f32 v121, v113, v119, v121
	v_lshlrev_b32_e32 v118, 16, v71
	v_and_b32_e32 v119, 0xffff0000, v71
	v_fma_f32 v122, v113, v118, v122
	v_fma_f32 v123, v113, v119, v123
	v_lshlrev_b32_e32 v118, 16, v72
	v_and_b32_e32 v119, 0xffff0000, v72
	v_fma_f32 v124, v113, v118, v124
	v_fma_f32 v125, v113, v119, v125
	v_lshlrev_b32_e32 v118, 16, v73
	v_and_b32_e32 v119, 0xffff0000, v73
	v_fma_f32 v126, v113, v118, v126
	v_fma_f32 v127, v113, v119, v127
	v_lshlrev_b32_e32 v118, 16, v74
	v_and_b32_e32 v119, 0xffff0000, v74
	v_add_f32_e32 v120, v120, v118
	v_add_f32_e32 v121, v121, v119
	v_lshlrev_b32_e32 v118, 16, v75
	v_and_b32_e32 v119, 0xffff0000, v75
	v_add_f32_e32 v122, v122, v118
	v_add_f32_e32 v123, v123, v119
	v_lshlrev_b32_e32 v118, 16, v76
	v_and_b32_e32 v119, 0xffff0000, v76
	v_add_f32_e32 v124, v124, v118
	v_add_f32_e32 v125, v125, v119
	v_lshlrev_b32_e32 v118, 16, v77
	v_and_b32_e32 v119, 0xffff0000, v77
	v_add_f32_e32 v126, v126, v118
	v_add_f32_e32 v127, v127, v119
	v_lshlrev_b32_e32 v118, 16, v78
	v_and_b32_e32 v119, 0xffff0000, v78
	v_fma_f32 v120, v113, v118, v120
	v_fma_f32 v121, v113, v119, v121
	v_lshlrev_b32_e32 v118, 16, v79
	v_and_b32_e32 v119, 0xffff0000, v79
	v_fma_f32 v122, v113, v118, v122
	v_fma_f32 v123, v113, v119, v123
	v_lshlrev_b32_e32 v118, 16, v80
	v_and_b32_e32 v119, 0xffff0000, v80
	v_fma_f32 v124, v113, v118, v124
	v_fma_f32 v125, v113, v119, v125
	v_lshlrev_b32_e32 v118, 16, v81
	v_and_b32_e32 v119, 0xffff0000, v81
	v_fma_f32 v126, v113, v118, v126
	v_fma_f32 v127, v113, v119, v127
	v_lshlrev_b32_e32 v118, 16, v82
	v_and_b32_e32 v119, 0xffff0000, v82
	v_add_f32_e32 v120, v120, v118
	v_add_f32_e32 v121, v121, v119
	v_lshlrev_b32_e32 v118, 16, v83
	v_and_b32_e32 v119, 0xffff0000, v83
	v_add_f32_e32 v122, v122, v118
	v_add_f32_e32 v123, v123, v119
	v_lshlrev_b32_e32 v118, 16, v84
	v_and_b32_e32 v119, 0xffff0000, v84
	v_add_f32_e32 v124, v124, v118
	v_add_f32_e32 v125, v125, v119
	v_lshlrev_b32_e32 v118, 16, v85
	v_and_b32_e32 v119, 0xffff0000, v85
	v_add_f32_e32 v126, v126, v118
	v_add_f32_e32 v127, v127, v119
	v_lshlrev_b32_e32 v118, 16, v86
	v_and_b32_e32 v119, 0xffff0000, v86
	v_fma_f32 v120, v113, v118, v120
	v_fma_f32 v121, v113, v119, v121
	v_lshlrev_b32_e32 v118, 16, v87
	v_and_b32_e32 v119, 0xffff0000, v87
	v_fma_f32 v122, v113, v118, v122
	v_fma_f32 v123, v113, v119, v123
	v_lshlrev_b32_e32 v118, 16, v88
	v_and_b32_e32 v119, 0xffff0000, v88
	v_fma_f32 v124, v113, v118, v124
	v_fma_f32 v125, v113, v119, v125
	v_lshlrev_b32_e32 v118, 16, v89
	v_and_b32_e32 v119, 0xffff0000, v89
	v_fma_f32 v126, v113, v118, v126
	v_fma_f32 v127, v113, v119, v127
	v_lshlrev_b32_e32 v118, 16, v90
	v_and_b32_e32 v119, 0xffff0000, v90
	v_add_f32_e32 v120, v120, v118
	v_add_f32_e32 v121, v121, v119
	v_lshlrev_b32_e32 v118, 16, v91
	v_and_b32_e32 v119, 0xffff0000, v91
	v_add_f32_e32 v122, v122, v118
	v_add_f32_e32 v123, v123, v119
	v_lshlrev_b32_e32 v118, 16, v92
	v_and_b32_e32 v119, 0xffff0000, v92
	v_add_f32_e32 v124, v124, v118
	v_add_f32_e32 v125, v125, v119
	v_lshlrev_b32_e32 v118, 16, v93
	v_and_b32_e32 v119, 0xffff0000, v93
	v_add_f32_e32 v126, v126, v118
	v_add_f32_e32 v127, v127, v119
	v_lshlrev_b32_e32 v118, 16, v94
	v_and_b32_e32 v119, 0xffff0000, v94
	v_fma_f32 v120, v113, v118, v120
	v_fma_f32 v121, v113, v119, v121
	v_lshlrev_b32_e32 v118, 16, v95
	v_and_b32_e32 v119, 0xffff0000, v95
	v_fma_f32 v122, v113, v118, v122
	v_fma_f32 v123, v113, v119, v123
	v_lshlrev_b32_e32 v118, 16, v96
	v_and_b32_e32 v119, 0xffff0000, v96
	v_fma_f32 v124, v113, v118, v124
	v_fma_f32 v125, v113, v119, v125
	v_lshlrev_b32_e32 v118, 16, v97
	v_and_b32_e32 v119, 0xffff0000, v97
	v_fma_f32 v126, v113, v118, v126
	v_fma_f32 v127, v113, v119, v127
	v_lshlrev_b32_e32 v118, 16, v98
	v_and_b32_e32 v119, 0xffff0000, v98
	v_mul_f32_e32 v120, v120, v118
	v_mul_f32_e32 v121, v121, v119
	v_cvt_pk_bf16_f32 v98, v120, v121
	v_lshlrev_b32_e32 v118, 16, v99
	v_and_b32_e32 v119, 0xffff0000, v99
	v_mul_f32_e32 v122, v122, v118
	v_mul_f32_e32 v123, v123, v119
	v_cvt_pk_bf16_f32 v99, v122, v123
	v_lshlrev_b32_e32 v118, 16, v100
	v_and_b32_e32 v119, 0xffff0000, v100
	v_mul_f32_e32 v124, v124, v118
	v_mul_f32_e32 v125, v125, v119
	v_cvt_pk_bf16_f32 v100, v124, v125
	v_lshlrev_b32_e32 v118, 16, v101
	v_and_b32_e32 v119, 0xffff0000, v101
	v_mul_f32_e32 v126, v126, v118
	v_mul_f32_e32 v127, v127, v119
	v_cvt_pk_bf16_f32 v101, v126, v127
	global_store_dwordx4 v112, v[98:101], s[44:45]
	s_branch .Ldftc_loop
